# gates epilogue: lam/ba/bi loads of blocks 1-3 and 5-7 hoisted next to blocks 0 and 4, six per-block vmcnt(0) waits removed
# speedup vs baseline: 1.0096x; 1.0016x over previous
.LBB0_329:
	s_ashr_i32 s49, s48, 31
	s_lshl_b64 s[42:43], s[48:49], 18
	s_add_u32 s42, s22, s42
	s_addc_u32 s43, s23, s43
	s_lshl_b32 s47, s46, 8
	s_and_b32 s49, s47, 0x300
	s_add_u32 s50, s42, s49
	s_addc_u32 s51, s43, 0
	s_and_b64 s[42:43], s[0:1], exec
	s_cselect_b32 s61, s51, s31
	s_cselect_b32 s60, s50, s30
	s_ashr_i32 s47, s46, 31
	s_lshl_b64 s[42:43], s[46:47], 18
	v_readlane_b32 s52, v253, 63
	v_readlane_b32 s53, v254, 0
	s_add_u32 s42, s52, s42
	s_addc_u32 s43, s53, s43
	s_add_u32 s52, s42, s49
	s_addc_u32 s53, s43, 0
	s_add_u32 s42, s30, 0x20080
	s_addc_u32 s43, s31, 0
	s_add_u32 s30, s60, 0x20000
	s_addc_u32 s31, s61, 0
	s_add_i32 s47, 0, 0x10000
	v_add_u32_e32 v12, s47, v194
	ds_read_b128 v[0:3], v12
	ds_read_b128 v[4:7], v12 offset:1024
	ds_read_b128 v[8:11], v12 offset:2048
	ds_read_b128 v[12:15], v12 offset:3072
	s_and_b64 s[0:1], s[0:1], exec
	s_cselect_b32 s0, s52, s58
	s_cselect_b32 s1, s53, s59
	s_add_u32 s58, s0, 0x20000
	s_addc_u32 s59, s1, 0
	v_lshl_add_u64 v[48:49], s[42:43], 0, v[96:97]
	s_add_i32 m0, s36, 0xc000
	ds_read_b128 v[16:19], v195
	ds_read_b128 v[20:23], v195 offset:1024
	ds_read_b128 v[24:27], v195 offset:2048
	ds_read_b128 v[28:31], v195 offset:3072
	ds_read_b128 v[32:35], v195 offset:4096
	ds_read_b128 v[36:39], v195 offset:5120
	ds_read_b128 v[40:43], v195 offset:6144
	ds_read_b128 v[44:47], v195 offset:7168
	global_load_lds_dwordx4 v[48:49], off
	v_lshl_add_u64 v[48:49], s[42:43], 0, v[130:131]
	s_add_i32 m0, s36, 0xe000
	s_nop 0
	global_load_lds_dwordx4 v[48:49], off
	s_waitcnt lgkmcnt(8)
	s_barrier
	s_waitcnt lgkmcnt(0)
	s_setprio 1
	s_waitcnt lgkmcnt(0)
	v_mfma_f32_16x16x32_bf16 v[56:59], v[0:3], v[24:27], 0
	v_mfma_f32_16x16x32_bf16 v[60:63], v[4:7], v[28:31], v[56:59]
	v_mfma_f32_16x16x32_bf16 v[56:59], v[8:11], v[24:27], 0
	v_mfma_f32_16x16x32_bf16 v[64:67], v[12:15], v[28:31], v[56:59]
	v_mfma_f32_16x16x32_bf16 v[56:59], v[0:3], v[32:35], 0
	v_mfma_f32_16x16x32_bf16 v[68:71], v[4:7], v[36:39], v[56:59]
	v_mfma_f32_16x16x32_bf16 v[56:59], v[8:11], v[32:35], 0
	v_mfma_f32_16x16x32_bf16 v[72:75], v[12:15], v[36:39], v[56:59]
	v_mfma_f32_16x16x32_bf16 v[56:59], v[0:3], v[40:43], 0
	v_mfma_f32_16x16x32_bf16 v[48:51], v[0:3], v[16:19], 0
	v_mfma_f32_16x16x32_bf16 v[52:55], v[8:11], v[16:19], 0
	v_mfma_f32_16x16x32_bf16 v[76:79], v[4:7], v[44:47], v[56:59]
	v_mfma_f32_16x16x32_bf16 v[56:59], v[8:11], v[40:43], 0
	v_mfma_f32_16x16x32_bf16 v[48:51], v[4:7], v[20:23], v[48:51]
	v_mfma_f32_16x16x32_bf16 v[52:55], v[12:15], v[20:23], v[52:55]
	v_mfma_f32_16x16x32_bf16 v[80:83], v[12:15], v[44:47], v[56:59]
	s_setprio 0
	s_barrier
	s_add_i32 s42, 0, 0x14000
	s_add_i32 s43, s47, s24
	v_add_u32_e32 v92, s42, v194
	v_lshl_add_u64 v[190:191], s[0:1], 0, v[96:97]
	s_mov_b32 m0, s43
	ds_read_b128 v[56:59], v92
	ds_read_b128 v[84:87], v92 offset:1024
	ds_read_b128 v[88:91], v92 offset:2048
	ds_read_b128 v[92:95], v92 offset:3072
	global_load_lds_dwordx4 v[190:191], off
	v_lshl_add_u64 v[248:249], s[0:1], 0, v[130:131]
	s_add_i32 m0, s43, 0x2000
	s_nop 0
	global_load_lds_dwordx4 v[248:249], off
	s_barrier
	s_waitcnt lgkmcnt(0)
	s_setprio 1
	s_waitcnt lgkmcnt(0)
	v_mfma_f32_16x16x32_bf16 v[98:101], v[56:59], v[16:19], 0
	v_mfma_f32_16x16x32_bf16 v[16:19], v[88:91], v[16:19], 0
	v_mfma_f32_16x16x32_bf16 v[98:101], v[84:87], v[20:23], v[98:101]
	v_mfma_f32_16x16x32_bf16 v[16:19], v[92:95], v[20:23], v[16:19]
	v_mfma_f32_16x16x32_bf16 v[20:23], v[56:59], v[24:27], 0
	v_mfma_f32_16x16x32_bf16 v[24:27], v[88:91], v[24:27], 0
	v_mfma_f32_16x16x32_bf16 v[20:23], v[84:87], v[28:31], v[20:23]
	v_mfma_f32_16x16x32_bf16 v[24:27], v[92:95], v[28:31], v[24:27]
	v_mfma_f32_16x16x32_bf16 v[28:31], v[56:59], v[32:35], 0
	v_mfma_f32_16x16x32_bf16 v[102:105], v[84:87], v[36:39], v[28:31]
	v_mfma_f32_16x16x32_bf16 v[28:31], v[88:91], v[32:35], 0
	v_mfma_f32_16x16x32_bf16 v[32:35], v[92:95], v[36:39], v[28:31]
	v_mfma_f32_16x16x32_bf16 v[28:31], v[56:59], v[40:43], 0
	v_mfma_f32_16x16x32_bf16 v[36:39], v[84:87], v[44:47], v[28:31]
	v_mfma_f32_16x16x32_bf16 v[28:31], v[88:91], v[40:43], 0
	v_mfma_f32_16x16x32_bf16 v[132:135], v[92:95], v[44:47], v[28:31]
	s_setprio 0
	s_mov_b32 m0, s36
	v_lshl_add_u64 v[164:165], s[60:61], 0, v[96:97]
	s_barrier
	s_nop 2
	ds_read_b128 v[28:31], v195 offset:16384
	ds_read_b128 v[40:43], v195 offset:17408
	ds_read_b128 v[44:47], v195 offset:18432
	ds_read_b128 v[106:109], v195 offset:19456
	ds_read_b128 v[110:113], v195 offset:20480
	ds_read_b128 v[114:117], v195 offset:21504
	ds_read_b128 v[118:121], v195 offset:22528
	ds_read_b128 v[122:125], v195 offset:23552
	global_load_lds_dwordx4 v[164:165], off
	v_lshl_add_u64 v[172:173], s[60:61], 0, v[130:131]
	s_mov_b32 m0, s37
	s_nop 0
	global_load_lds_dwordx4 v[172:173], off
	s_barrier
	s_waitcnt lgkmcnt(0)
	s_setprio 1
	s_waitcnt lgkmcnt(0)
	v_mfma_f32_16x16x32_bf16 v[126:129], v[0:3], v[28:31], 0
	v_mfma_f32_16x16x32_bf16 v[136:139], v[4:7], v[40:43], v[126:129]
	v_mfma_f32_16x16x32_bf16 v[126:129], v[8:11], v[28:31], 0
	v_mfma_f32_16x16x32_bf16 v[140:143], v[12:15], v[40:43], v[126:129]
	v_mfma_f32_16x16x32_bf16 v[126:129], v[0:3], v[44:47], 0
	v_mfma_f32_16x16x32_bf16 v[144:147], v[4:7], v[106:109], v[126:129]
	v_mfma_f32_16x16x32_bf16 v[126:129], v[8:11], v[44:47], 0
	v_mfma_f32_16x16x32_bf16 v[148:151], v[12:15], v[106:109], v[126:129]
	v_mfma_f32_16x16x32_bf16 v[126:129], v[0:3], v[110:113], 0
	v_mfma_f32_16x16x32_bf16 v[0:3], v[0:3], v[118:121], 0
	v_mfma_f32_16x16x32_bf16 v[152:155], v[4:7], v[114:117], v[126:129]
	v_mfma_f32_16x16x32_bf16 v[0:3], v[4:7], v[122:125], v[0:3]
	v_mfma_f32_16x16x32_bf16 v[4:7], v[8:11], v[118:121], 0
	v_mfma_f32_16x16x32_bf16 v[126:129], v[8:11], v[110:113], 0
	v_mfma_f32_16x16x32_bf16 v[4:7], v[12:15], v[122:125], v[4:7]
	v_mfma_f32_16x16x32_bf16 v[156:159], v[12:15], v[114:117], v[126:129]
	s_setprio 0
	s_barrier
	s_add_i32 s42, s42, s24
	v_lshl_add_u64 v[8:9], s[58:59], 0, v[96:97]
	s_mov_b32 m0, s42
	s_nop 0
	global_load_lds_dwordx4 v[8:9], off
	v_lshl_add_u64 v[8:9], s[58:59], 0, v[130:131]
	s_add_i32 m0, s42, 0x2000
	s_nop 0
	global_load_lds_dwordx4 v[8:9], off
	s_waitcnt vmcnt(6)
	s_barrier
	s_setprio 1
	v_mfma_f32_16x16x32_bf16 v[8:11], v[56:59], v[28:31], 0
	v_mfma_f32_16x16x32_bf16 v[12:15], v[84:87], v[40:43], v[8:11]
	v_mfma_f32_16x16x32_bf16 v[8:11], v[88:91], v[28:31], 0
	v_mfma_f32_16x16x32_bf16 v[174:177], v[92:95], v[40:43], v[8:11]
	v_mfma_f32_16x16x32_bf16 v[8:11], v[56:59], v[44:47], 0
	v_mfma_f32_16x16x32_bf16 v[178:181], v[84:87], v[106:109], v[8:11]
	v_mfma_f32_16x16x32_bf16 v[8:11], v[88:91], v[44:47], 0
	v_mfma_f32_16x16x32_bf16 v[182:185], v[92:95], v[106:109], v[8:11]
	v_mfma_f32_16x16x32_bf16 v[8:11], v[56:59], v[110:113], 0
	v_mfma_f32_16x16x32_bf16 v[186:189], v[84:87], v[114:117], v[8:11]
	v_mfma_f32_16x16x32_bf16 v[8:11], v[88:91], v[110:113], 0
	v_mfma_f32_16x16x32_bf16 v[196:199], v[92:95], v[114:117], v[8:11]
	v_mfma_f32_16x16x32_bf16 v[8:11], v[56:59], v[118:121], 0
	v_mfma_f32_16x16x32_bf16 v[200:203], v[84:87], v[122:125], v[8:11]
	v_mfma_f32_16x16x32_bf16 v[8:11], v[88:91], v[118:121], 0
	v_mfma_f32_16x16x32_bf16 v[228:231], v[92:95], v[122:125], v[8:11]
	s_setprio 0
	s_add_i32 s42, 0, 0x18000
	s_nop 4
	v_add_u32_e32 v8, s42, v194
	s_barrier
	ds_read_b128 v[84:87], v8
	ds_read_b128 v[232:235], v8 offset:1024
	ds_read_b128 v[236:239], v8 offset:2048
	ds_read_b128 v[240:243], v8 offset:3072
	s_mov_b32 m0, s68
	v_lshl_add_u64 v[28:29], s[30:31], 0, v[96:97]
	ds_read_b128 v[8:11], v195 offset:32768
	ds_read_b128 v[44:47], v195 offset:33792
	ds_read_b128 v[88:91], v195 offset:34816
	ds_read_b128 v[110:113], v195 offset:35840
	ds_read_b128 v[244:247], v195 offset:36864
	ds_read_b128 v[220:223], v195 offset:37888
	ds_read_b128 v[166:169], v195 offset:38912
	ds_read_b128 v[160:163], v195 offset:39936
	global_load_lds_dwordx4 v[28:29], off
	v_lshl_add_u64 v[28:29], s[30:31], 0, v[130:131]
	s_mov_b32 m0, s69
	s_nop 0
	global_load_lds_dwordx4 v[28:29], off
	s_waitcnt lgkmcnt(8)
	s_barrier
	s_waitcnt lgkmcnt(0)
	s_setprio 1
	s_waitcnt lgkmcnt(0)
	v_mfma_f32_16x16x32_bf16 v[28:31], v[84:87], v[8:11], v[48:51]
	v_mfma_f32_16x16x32_bf16 v[122:125], v[232:235], v[44:47], v[28:31]
	v_mfma_f32_16x16x32_bf16 v[28:31], v[236:239], v[8:11], v[52:55]
	v_mfma_f32_16x16x32_bf16 v[56:59], v[240:243], v[44:47], v[28:31]
	v_mfma_f32_16x16x32_bf16 v[28:31], v[84:87], v[88:91], v[60:63]
	v_mfma_f32_16x16x32_bf16 v[114:117], v[232:235], v[110:113], v[28:31]
	v_mfma_f32_16x16x32_bf16 v[28:31], v[236:239], v[88:91], v[64:67]
	v_mfma_f32_16x16x32_bf16 v[48:51], v[240:243], v[110:113], v[28:31]
	v_mfma_f32_16x16x32_bf16 v[28:31], v[84:87], v[244:247], v[68:71]
	v_mfma_f32_16x16x32_bf16 v[106:109], v[232:235], v[220:223], v[28:31]
	v_mfma_f32_16x16x32_bf16 v[28:31], v[236:239], v[244:247], v[72:75]
	v_mfma_f32_16x16x32_bf16 v[40:43], v[240:243], v[220:223], v[28:31]
	v_mfma_f32_16x16x32_bf16 v[28:31], v[84:87], v[166:169], v[76:79]
	v_mfma_f32_16x16x32_bf16 v[92:95], v[232:235], v[160:163], v[28:31]
	v_mfma_f32_16x16x32_bf16 v[28:31], v[236:239], v[166:169], v[80:83]
	v_mfma_f32_16x16x32_bf16 v[28:31], v[240:243], v[160:163], v[28:31]
	s_setprio 0
	s_barrier
	s_add_i32 s30, 0, 0x1c000
	v_add_u32_e32 v52, s30, v194
	s_add_i32 s31, s42, s24
	ds_read_b128 v[68:71], v52
	ds_read_b128 v[224:227], v52 offset:1024
	ds_read_b128 v[206:209], v52 offset:2048
	ds_read_b128 v[216:219], v52 offset:3072
	v_lshl_add_u64 v[52:53], v[190:191], 0, s[56:57]
	s_mov_b32 m0, s31
	s_nop 0
	global_load_lds_dwordx4 v[52:53], off
	v_lshl_add_u64 v[52:53], v[248:249], 0, s[56:57]
	s_add_i32 m0, s31, 0x2000
	s_nop 0
	global_load_lds_dwordx4 v[52:53], off
	s_barrier
	s_waitcnt lgkmcnt(0)
	s_setprio 1
	s_waitcnt lgkmcnt(0)
	v_mfma_f32_16x16x32_bf16 v[52:55], v[68:71], v[8:11], v[98:101]
	v_mfma_f32_16x16x32_bf16 v[8:11], v[206:209], v[8:11], v[16:19]
	v_mfma_f32_16x16x32_bf16 v[60:63], v[216:219], v[44:47], v[8:11]
	v_mfma_f32_16x16x32_bf16 v[8:11], v[68:71], v[88:91], v[20:23]
	v_mfma_f32_16x16x32_bf16 v[118:121], v[224:227], v[110:113], v[8:11]
	v_mfma_f32_16x16x32_bf16 v[8:11], v[206:209], v[88:91], v[24:27]
	v_mfma_f32_16x16x32_bf16 v[126:129], v[224:227], v[44:47], v[52:55]
	v_mfma_f32_16x16x32_bf16 v[52:55], v[216:219], v[110:113], v[8:11]
	v_mfma_f32_16x16x32_bf16 v[8:11], v[68:71], v[244:247], v[102:105]
	v_mfma_f32_16x16x32_bf16 v[110:113], v[224:227], v[220:223], v[8:11]
	v_mfma_f32_16x16x32_bf16 v[8:11], v[206:209], v[244:247], v[32:35]
	v_mfma_f32_16x16x32_bf16 v[44:47], v[216:219], v[220:223], v[8:11]
	v_mfma_f32_16x16x32_bf16 v[8:11], v[68:71], v[166:169], v[36:39]
	v_mfma_f32_16x16x32_bf16 v[102:105], v[224:227], v[160:163], v[8:11]
	v_mfma_f32_16x16x32_bf16 v[8:11], v[206:209], v[166:169], v[132:135]
	v_mfma_f32_16x16x32_bf16 v[36:39], v[216:219], v[160:163], v[8:11]
	s_setprio 0
	s_mov_b32 m0, s70
	s_nop 4
	v_lshl_add_u64 v[8:9], v[164:165], 0, s[56:57]
	s_barrier
	ds_read_b128 v[20:23], v195 offset:49152
	ds_read_b128 v[32:35], v195 offset:50176
	ds_read_b128 v[76:79], v195 offset:51200
	ds_read_b128 v[132:135], v195 offset:52224
	ds_read_b128 v[160:163], v195 offset:53248
	ds_read_b128 v[166:169], v195 offset:54272
	ds_read_b128 v[220:223], v195 offset:55296
	ds_read_b128 v[244:247], v195 offset:56320
	global_load_lds_dwordx4 v[8:9], off
	v_lshl_add_u64 v[8:9], v[172:173], 0, s[56:57]
	s_mov_b32 m0, s71
	s_nop 0
	global_load_lds_dwordx4 v[8:9], off
	s_barrier
	s_waitcnt lgkmcnt(0)
	s_setprio 1
	s_waitcnt lgkmcnt(0)
	v_mfma_f32_16x16x32_bf16 v[8:11], v[84:87], v[20:23], v[136:139]
	s_add_u32 s0, s0, 0x20080
	s_addc_u32 s1, s1, 0
	v_mfma_f32_16x16x32_bf16 v[88:91], v[232:235], v[32:35], v[8:11]
	v_mfma_f32_16x16x32_bf16 v[8:11], v[236:239], v[20:23], v[140:143]
	v_mfma_f32_16x16x32_bf16 v[24:27], v[240:243], v[32:35], v[8:11]
	v_mfma_f32_16x16x32_bf16 v[8:11], v[84:87], v[76:79], v[144:147]
	v_mfma_f32_16x16x32_bf16 v[80:83], v[232:235], v[132:135], v[8:11]
	v_mfma_f32_16x16x32_bf16 v[8:11], v[236:239], v[76:79], v[148:151]
	v_mfma_f32_16x16x32_bf16 v[16:19], v[240:243], v[132:135], v[8:11]
	v_mfma_f32_16x16x32_bf16 v[8:11], v[84:87], v[160:163], v[152:155]
	v_mfma_f32_16x16x32_bf16 v[0:3], v[84:87], v[220:223], v[0:3]
	v_mfma_f32_16x16x32_bf16 v[72:75], v[232:235], v[166:169], v[8:11]
	v_mfma_f32_16x16x32_bf16 v[8:11], v[236:239], v[160:163], v[156:159]
	v_mfma_f32_16x16x32_bf16 v[64:67], v[232:235], v[244:247], v[0:3]
	v_mfma_f32_16x16x32_bf16 v[0:3], v[236:239], v[220:223], v[4:7]
	v_mfma_f32_16x16x32_bf16 v[8:11], v[240:243], v[166:169], v[8:11]
	v_mfma_f32_16x16x32_bf16 v[0:3], v[240:243], v[244:247], v[0:3]
	s_setprio 0
	s_barrier
	s_add_i32 s30, s30, s24
	v_lshl_add_u64 v[4:5], s[0:1], 0, v[96:97]
	s_mov_b32 m0, s30
	s_nop 0
	global_load_lds_dwordx4 v[4:5], off
	v_lshl_add_u64 v[4:5], s[0:1], 0, v[130:131]
	s_add_i32 m0, s30, 0x2000
	s_nop 0
	global_load_lds_dwordx4 v[4:5], off
	s_waitcnt vmcnt(6)
	s_barrier
	s_setprio 1
	v_mfma_f32_16x16x32_bf16 v[4:7], v[68:71], v[20:23], v[12:15]
	v_mfma_f32_16x16x32_bf16 v[98:101], v[224:227], v[32:35], v[4:7]
	v_mfma_f32_16x16x32_bf16 v[4:7], v[206:209], v[20:23], v[174:177]
	v_mfma_f32_16x16x32_bf16 v[32:35], v[216:219], v[32:35], v[4:7]
	v_mfma_f32_16x16x32_bf16 v[4:7], v[68:71], v[76:79], v[178:181]
	v_mfma_f32_16x16x32_bf16 v[84:87], v[224:227], v[132:135], v[4:7]
	v_mfma_f32_16x16x32_bf16 v[4:7], v[206:209], v[76:79], v[182:185]
	v_mfma_f32_16x16x32_bf16 v[20:23], v[216:219], v[132:135], v[4:7]
	v_mfma_f32_16x16x32_bf16 v[4:7], v[68:71], v[160:163], v[186:189]
	v_mfma_f32_16x16x32_bf16 v[76:79], v[224:227], v[166:169], v[4:7]
	v_mfma_f32_16x16x32_bf16 v[4:7], v[206:209], v[160:163], v[196:199]
	v_mfma_f32_16x16x32_bf16 v[12:15], v[216:219], v[166:169], v[4:7]
	v_mfma_f32_16x16x32_bf16 v[4:7], v[68:71], v[220:223], v[200:203]
	v_mfma_f32_16x16x32_bf16 v[68:71], v[224:227], v[244:247], v[4:7]
	v_mfma_f32_16x16x32_bf16 v[4:7], v[206:209], v[220:223], v[228:231]
	v_mfma_f32_16x16x32_bf16 v[4:7], v[216:219], v[244:247], v[4:7]
	s_setprio 0
	s_lshl_b32 s0, s76, 7
	s_and_b32 s0, s0, 0x180
	v_mov_b32_e32 v132, v193
	v_mov_b32_e32 v139, v192
	s_or_b32 s0, s0, s73
	s_barrier
	s_ashr_i32 s30, s76, 2
	v_lshl_add_u32 v138, v132, 2, s0
	v_lshl_add_u32 v132, s30, 9, v138
	v_ashrrev_i32_e32 v133, 31, v132
	v_readlane_b32 s4, v255, 10
	v_lshlrev_b64 v[136:137], 2, v[132:133]
	v_readlane_b32 s18, v255, 24
	v_readlane_b32 s19, v255, 25
	v_readlane_b32 s12, v255, 18
	v_readlane_b32 s13, v255, 19
	v_readlane_b32 s16, v255, 22
	v_readlane_b32 s17, v255, 23
	v_lshl_add_u64 v[134:135], s[18:19], 0, v[136:137]
	v_lshl_add_u64 v[132:133], s[12:13], 0, v[136:137]
	global_load_dword v140, v[134:135], off
	v_lshl_add_u64 v[136:137], s[16:17], 0, v[136:137]
	global_load_dword v196, v[132:133], off
	global_load_dword v197, v[136:137], off
	global_load_dword v232, v[134:135], off offset:4
	global_load_dword v199, v[132:133], off offset:4
	global_load_dword v198, v[136:137], off offset:4
	global_load_dword v233, v[134:135], off offset:8
	global_load_dword v201, v[132:133], off offset:8
	global_load_dword v200, v[136:137], off offset:8
	global_load_dword v234, v[134:135], off offset:12
	global_load_dword v203, v[132:133], off offset:12
	global_load_dword v202, v[136:137], off offset:12
	s_mov_b32 s0, 0xc1700000
	v_readlane_b32 s5, v255, 11
	v_readlane_b32 s6, v255, 12
	v_readlane_b32 s7, v255, 13
	v_readlane_b32 s8, v255, 14
	v_readlane_b32 s9, v255, 15
	v_readlane_b32 s10, v255, 16
	v_readlane_b32 s11, v255, 17
	v_readlane_b32 s14, v255, 20
	v_readlane_b32 s15, v255, 21
	s_waitcnt vmcnt(0)
	v_xor_b32_e32 v152, 0x80000000, v140
	v_cmp_ngt_f32_e32 vcc, s0, v140
	s_mov_b64 s[0:1], exec
	s_and_b64 s[42:43], s[0:1], vcc
	s_xor_b64 s[0:1], s[42:43], s[0:1]
	v_mov_b32_e32 v218, v171
	s_mov_b64 exec, s[42:43]
	s_cbranch_execz .LBB0_331
	v_mul_f32_e32 v140, 0xbfb8aa3b, v140
	v_exp_f32_e32 v154, v140
	s_mov_b32 s31, 0x3f2aaaab
	v_add_f32_e32 v142, 1.0, v154
	v_frexp_mant_f32_e32 v144, v142
	v_cvt_f64_f32_e32 v[140:141], v142
	v_frexp_exp_i32_f64_e32 v140, v[140:141]
	v_cmp_gt_f32_e32 vcc, s31, v144
	v_add_f32_e32 v143, -1.0, v142
	v_sub_f32_e32 v145, v143, v142
	v_subbrev_co_u32_e32 v148, vcc, 0, v140, vcc
	v_sub_u32_e32 v140, 0, v148
	v_sub_f32_e32 v143, v154, v143
	v_add_f32_e32 v145, 1.0, v145
	v_ldexp_f32 v141, v142, v140
	v_add_f32_e32 v143, v143, v145
	v_add_f32_e32 v142, -1.0, v141
	v_add_f32_e32 v144, 1.0, v141
	v_ldexp_f32 v140, v143, v140
	v_add_f32_e32 v143, 1.0, v142
	v_add_f32_e32 v145, -1.0, v144
	v_sub_f32_e32 v143, v141, v143
	v_sub_f32_e32 v141, v141, v145
	v_add_f32_e32 v143, v140, v143
	v_add_f32_e32 v140, v140, v141
	v_add_f32_e32 v149, v144, v140
	v_rcp_f32_e32 v151, v149
	v_sub_f32_e32 v141, v149, v144
	v_sub_f32_e32 v150, v140, v141
	v_add_f32_e32 v141, v142, v143
	v_mul_f32_e32 v153, v141, v151
	v_sub_f32_e32 v140, v141, v142
	v_mul_f32_e32 v142, v149, v153
	v_fma_f32 v144, v153, v149, -v142
	v_fmac_f32_e32 v144, v153, v150
	v_sub_f32_e32 v152, v143, v140
	v_add_f32_e32 v140, v142, v144
	v_sub_f32_e32 v143, v141, v140
	v_pk_add_f32 v[146:147], v[140:141], v[142:143] neg_lo:[0,1] neg_hi:[0,1]
	v_mov_b32_e32 v145, v140
	v_pk_add_f32 v[140:141], v[146:147], v[144:145] neg_lo:[0,1] neg_hi:[0,1]
	s_mov_b32 s31, 0x3f317218
	v_add_f32_e32 v141, v152, v141
	v_add_f32_e32 v140, v140, v141
	v_add_f32_e32 v141, v143, v140
	v_mul_f32_e32 v152, v151, v141
	v_mul_f32_e32 v142, v149, v152
	v_fma_f32 v144, v152, v149, -v142
	v_fmac_f32_e32 v144, v152, v150
	v_sub_f32_e32 v143, v143, v141
	v_add_f32_e32 v149, v140, v143
	v_add_f32_e32 v140, v142, v144
	v_sub_f32_e32 v143, v141, v140
	v_pk_add_f32 v[146:147], v[140:141], v[142:143] neg_lo:[0,1] neg_hi:[0,1]
	v_mov_b32_e32 v145, v140
	v_pk_add_f32 v[140:141], v[146:147], v[144:145] neg_lo:[0,1] neg_hi:[0,1]
	s_nop 0
	v_add_f32_e32 v141, v149, v141
	v_add_f32_e32 v140, v140, v141
	v_add_f32_e32 v141, v153, v152
	v_add_f32_e32 v140, v143, v140
	v_sub_f32_e32 v142, v141, v153
	v_mul_f32_e32 v140, v151, v140
	v_sub_f32_e32 v142, v152, v142
	v_add_f32_e32 v142, v142, v140
	v_add_f32_e32 v144, v141, v142
	v_mul_f32_e32 v145, v144, v144
	v_fmamk_f32 v140, v145, 0x3e9b6dac, v218
	v_fmaak_f32 v171, v145, v140, 0x3f2aaada
	v_cvt_f32_i32_e32 v140, v148
	v_sub_f32_e32 v141, v144, v141
	v_sub_f32_e32 v141, v142, v141
	v_ldexp_f32 v146, v141, 1
	v_mul_f32_e32 v141, v144, v145
	v_ldexp_f32 v143, v144, 1
	v_pk_mul_f32 v[144:145], v[140:141], v[170:171]
	s_nop 0
	v_fma_f32 v142, v140, s31, -v144
	v_fmac_f32_e32 v142, 0xb102e308, v140
	v_pk_add_f32 v[140:141], v[144:145], v[142:143]
	s_mov_b32 s31, 0x7f800000
	v_sub_f32_e32 v143, v141, v143
	v_sub_f32_e32 v143, v145, v143
	v_add_f32_e32 v147, v146, v143
	v_mov_b32_e32 v146, v144
	v_pk_add_f32 v[144:145], v[140:141], v[144:145] neg_lo:[0,1] neg_hi:[0,1]
	v_pk_add_f32 v[148:149], v[140:141], v[146:147]
	v_mov_b32_e32 v143, v140
	v_mov_b32_e32 v145, v149
	v_pk_add_f32 v[150:151], v[142:143], v[144:145] neg_lo:[0,1] neg_hi:[0,1]
	v_pk_add_f32 v[142:143], v[142:143], v[144:145]
	v_mov_b32_e32 v146, v147
	v_pk_add_f32 v[144:145], v[142:143], v[140:141] op_sel:[1,0] op_sel_hi:[0,1] neg_lo:[0,1] neg_hi:[0,1]
	v_pk_add_f32 v[152:153], v[148:149], v[144:145] op_sel_hi:[1,0] neg_lo:[0,1] neg_hi:[0,1]
	v_mov_b32_e32 v148, v149
	v_mov_b32_e32 v149, v143
	v_pk_mov_b32 v[144:145], v[140:141], v[144:145] op_sel:[1,0]
	v_mov_b32_e32 v147, v140
	v_pk_add_f32 v[144:145], v[148:149], v[144:145] neg_lo:[0,1] neg_hi:[0,1]
	v_mov_b32_e32 v152, v150
	v_pk_add_f32 v[140:141], v[146:147], v[144:145] neg_lo:[0,1] neg_hi:[0,1]
	v_mov_b32_e32 v151, v143
	v_pk_add_f32 v[144:145], v[152:153], v[140:141]
	v_cmp_neq_f32_e32 vcc, s31, v154
	v_pk_add_f32 v[146:147], v[144:145], v[144:145] op_sel:[0,1] op_sel_hi:[1,0]
	s_mov_b32 s31, 0x33800000
	v_pk_add_f32 v[142:143], v[142:143], v[146:147] op_sel:[1,0] op_sel_hi:[0,1]
	v_mov_b32_e32 v145, v142
	v_pk_add_f32 v[148:149], v[144:145], v[150:151] neg_lo:[0,1] neg_hi:[0,1]
	v_mov_b32_e32 v141, v146
	v_sub_f32_e32 v143, v144, v148
	v_pk_add_f32 v[140:141], v[140:141], v[148:149] neg_lo:[0,1] neg_hi:[0,1]
	v_sub_f32_e32 v143, v150, v143
	v_add_f32_e32 v140, v140, v143
	v_add_f32_e32 v140, v140, v141
	v_add_f32_e32 v140, v142, v140
	v_cndmask_b32_e32 v140, v214, v140, vcc
	v_cmp_ngt_f32_e32 vcc, -1.0, v154
	s_nop 1
	v_cndmask_b32_e32 v140, v215, v140, vcc
	v_cmp_neq_f32_e32 vcc, -1.0, v154
	s_nop 1
	v_cndmask_b32_e32 v140, v213, v140, vcc
	v_cmp_lt_f32_e64 vcc, |v154|, s31
	s_nop 1
	v_cndmask_b32_e32 v152, v140, v154, vcc
.LBB0_331:
	s_andn2_saveexec_b64 s[0:1], s[0:1]
	s_or_b64 exec, exec, s[0:1]
	s_mov_b32 s0, 0xc1700000
	v_xor_b32_e32 v153, 0x80000000, v232
	v_cmp_ngt_f32_e32 vcc, s0, v232
	s_mov_b64 s[0:1], exec
	s_and_b64 s[42:43], s[0:1], vcc
	s_xor_b64 s[0:1], s[42:43], s[0:1]
	v_mov_b32_e32 v248, v211
	v_mov_b32_e32 v249, v205
	s_mov_b64 exec, s[42:43]
	s_cbranch_execz .LBB0_333
	v_mul_f32_e32 v140, 0xbfb8aa3b, v232
	v_exp_f32_e32 v153, v140
	s_mov_b32 s31, 0x3f2aaaab
	v_add_f32_e32 v142, 1.0, v153
	v_frexp_mant_f32_e32 v144, v142
	v_cvt_f64_f32_e32 v[140:141], v142
	v_frexp_exp_i32_f64_e32 v140, v[140:141]
	v_cmp_gt_f32_e32 vcc, s31, v144
	v_add_f32_e32 v143, -1.0, v142
	v_sub_f32_e32 v145, v143, v142
	v_subbrev_co_u32_e32 v148, vcc, 0, v140, vcc
	v_sub_u32_e32 v140, 0, v148
	v_sub_f32_e32 v143, v153, v143
	v_add_f32_e32 v145, 1.0, v145
	v_ldexp_f32 v141, v142, v140
	v_add_f32_e32 v143, v143, v145
	v_add_f32_e32 v142, -1.0, v141
	v_add_f32_e32 v144, 1.0, v141
	v_ldexp_f32 v140, v143, v140
	v_add_f32_e32 v143, 1.0, v142
	v_add_f32_e32 v145, -1.0, v144
	v_sub_f32_e32 v143, v141, v143
	v_sub_f32_e32 v141, v141, v145
	v_add_f32_e32 v143, v140, v143
	v_add_f32_e32 v140, v140, v141
	v_add_f32_e32 v149, v144, v140
	v_rcp_f32_e32 v151, v149
	v_sub_f32_e32 v141, v149, v144
	v_sub_f32_e32 v150, v140, v141
	v_add_f32_e32 v141, v142, v143
	v_mul_f32_e32 v155, v141, v151
	v_sub_f32_e32 v140, v141, v142
	v_mul_f32_e32 v142, v149, v155
	v_fma_f32 v144, v155, v149, -v142
	v_fmac_f32_e32 v144, v155, v150
	v_sub_f32_e32 v154, v143, v140
	v_add_f32_e32 v140, v142, v144
	v_sub_f32_e32 v143, v141, v140
	v_pk_add_f32 v[146:147], v[140:141], v[142:143] neg_lo:[0,1] neg_hi:[0,1]
	v_mov_b32_e32 v145, v140
	v_pk_add_f32 v[140:141], v[146:147], v[144:145] neg_lo:[0,1] neg_hi:[0,1]
	s_mov_b32 s31, 0x3f317218
	v_add_f32_e32 v141, v154, v141
	v_add_f32_e32 v140, v140, v141
	v_add_f32_e32 v141, v143, v140
	v_mul_f32_e32 v154, v151, v141
	v_mul_f32_e32 v142, v149, v154
	v_fma_f32 v144, v154, v149, -v142
	v_fmac_f32_e32 v144, v154, v150
	v_sub_f32_e32 v143, v143, v141
	v_add_f32_e32 v149, v140, v143
	v_add_f32_e32 v140, v142, v144
	v_sub_f32_e32 v143, v141, v140
	v_pk_add_f32 v[146:147], v[140:141], v[142:143] neg_lo:[0,1] neg_hi:[0,1]
	v_mov_b32_e32 v145, v140
	v_pk_add_f32 v[140:141], v[146:147], v[144:145] neg_lo:[0,1] neg_hi:[0,1]
	s_nop 0
	v_add_f32_e32 v141, v149, v141
	v_add_f32_e32 v140, v140, v141
	v_add_f32_e32 v141, v155, v154
	v_add_f32_e32 v140, v143, v140
	v_sub_f32_e32 v142, v141, v155
	v_mul_f32_e32 v140, v151, v140
	v_sub_f32_e32 v142, v154, v142
	v_add_f32_e32 v142, v142, v140
	v_add_f32_e32 v144, v141, v142
	v_mul_f32_e32 v145, v144, v144
	v_fmamk_f32 v140, v145, 0x3e9b6dac, v218
	v_fmaak_f32 v171, v145, v140, 0x3f2aaada
	v_cvt_f32_i32_e32 v140, v148
	v_sub_f32_e32 v141, v144, v141
	v_sub_f32_e32 v141, v142, v141
	v_ldexp_f32 v146, v141, 1
	v_mul_f32_e32 v141, v144, v145
	v_ldexp_f32 v143, v144, 1
	v_pk_mul_f32 v[144:145], v[140:141], v[170:171]
	s_nop 0
	v_fma_f32 v142, v140, s31, -v144
	v_fmac_f32_e32 v142, 0xb102e308, v140
	v_pk_add_f32 v[140:141], v[144:145], v[142:143]
	s_mov_b32 s31, 0x7f800000
	v_sub_f32_e32 v143, v141, v143
	v_sub_f32_e32 v143, v145, v143
	v_add_f32_e32 v147, v146, v143
	v_mov_b32_e32 v146, v144
	v_pk_add_f32 v[144:145], v[140:141], v[144:145] neg_lo:[0,1] neg_hi:[0,1]
	v_pk_add_f32 v[148:149], v[140:141], v[146:147]
	v_mov_b32_e32 v143, v140
	v_mov_b32_e32 v145, v149
	v_pk_add_f32 v[150:151], v[142:143], v[144:145] neg_lo:[0,1] neg_hi:[0,1]
	v_pk_add_f32 v[142:143], v[142:143], v[144:145]
	v_mov_b32_e32 v146, v147
	v_pk_add_f32 v[144:145], v[142:143], v[140:141] op_sel:[1,0] op_sel_hi:[0,1] neg_lo:[0,1] neg_hi:[0,1]
	v_pk_add_f32 v[154:155], v[148:149], v[144:145] op_sel_hi:[1,0] neg_lo:[0,1] neg_hi:[0,1]
	v_mov_b32_e32 v148, v149
	v_mov_b32_e32 v149, v143
	v_pk_mov_b32 v[144:145], v[140:141], v[144:145] op_sel:[1,0]
	v_mov_b32_e32 v147, v140
	v_pk_add_f32 v[144:145], v[148:149], v[144:145] neg_lo:[0,1] neg_hi:[0,1]
	v_mov_b32_e32 v154, v150
	v_pk_add_f32 v[140:141], v[146:147], v[144:145] neg_lo:[0,1] neg_hi:[0,1]
	v_mov_b32_e32 v151, v143
	v_pk_add_f32 v[144:145], v[154:155], v[140:141]
	v_cmp_neq_f32_e32 vcc, s31, v153
	v_pk_add_f32 v[146:147], v[144:145], v[144:145] op_sel:[0,1] op_sel_hi:[1,0]
	s_mov_b32 s31, 0x33800000
	v_pk_add_f32 v[142:143], v[142:143], v[146:147] op_sel:[1,0] op_sel_hi:[0,1]
	v_mov_b32_e32 v145, v142
	v_pk_add_f32 v[148:149], v[144:145], v[150:151] neg_lo:[0,1] neg_hi:[0,1]
	v_mov_b32_e32 v141, v146
	v_sub_f32_e32 v143, v144, v148
	v_pk_add_f32 v[140:141], v[140:141], v[148:149] neg_lo:[0,1] neg_hi:[0,1]
	v_sub_f32_e32 v143, v150, v143
	v_add_f32_e32 v140, v140, v143
	v_add_f32_e32 v140, v140, v141
	v_add_f32_e32 v140, v142, v140
	v_cndmask_b32_e32 v140, v214, v140, vcc
	v_cmp_ngt_f32_e32 vcc, -1.0, v153
	s_nop 1
	v_cndmask_b32_e32 v140, v215, v140, vcc
	v_cmp_neq_f32_e32 vcc, -1.0, v153
	s_nop 1
	v_cndmask_b32_e32 v140, v213, v140, vcc
	v_cmp_lt_f32_e64 vcc, |v153|, s31
	s_nop 1
	v_cndmask_b32_e32 v153, v140, v153, vcc
.LBB0_333:
	s_andn2_saveexec_b64 s[0:1], s[0:1]
	s_or_b64 exec, exec, s[0:1]
	s_mov_b32 s0, 0xc1700000
	v_cmp_ngt_f32_e32 vcc, s0, v233
	v_xor_b32_e32 v154, 0x80000000, v233
	s_and_saveexec_b64 s[0:1], vcc
	s_xor_b64 s[0:1], exec, s[0:1]
	s_cbranch_execz .LBB0_335
	v_mul_f32_e32 v140, 0xbfb8aa3b, v233
	v_exp_f32_e32 v156, v140
	s_mov_b32 s31, 0x3f2aaaab
	v_add_f32_e32 v142, 1.0, v156
	v_frexp_mant_f32_e32 v144, v142
	v_cvt_f64_f32_e32 v[140:141], v142
	v_frexp_exp_i32_f64_e32 v140, v[140:141]
	v_cmp_gt_f32_e32 vcc, s31, v144
	v_add_f32_e32 v143, -1.0, v142
	v_sub_f32_e32 v145, v143, v142
	v_subbrev_co_u32_e32 v148, vcc, 0, v140, vcc
	v_sub_u32_e32 v140, 0, v148
	v_sub_f32_e32 v143, v156, v143
	v_add_f32_e32 v145, 1.0, v145
	v_ldexp_f32 v141, v142, v140
	v_add_f32_e32 v143, v143, v145
	v_add_f32_e32 v142, -1.0, v141
	v_add_f32_e32 v144, 1.0, v141
	v_ldexp_f32 v140, v143, v140
	v_add_f32_e32 v143, 1.0, v142
	v_add_f32_e32 v145, -1.0, v144
	v_sub_f32_e32 v143, v141, v143
	v_sub_f32_e32 v141, v141, v145
	v_add_f32_e32 v143, v140, v143
	v_add_f32_e32 v140, v140, v141
	v_add_f32_e32 v149, v144, v140
	v_rcp_f32_e32 v151, v149
	v_sub_f32_e32 v141, v149, v144
	v_sub_f32_e32 v150, v140, v141
	v_add_f32_e32 v141, v142, v143
	v_mul_f32_e32 v155, v141, v151
	v_sub_f32_e32 v140, v141, v142
	v_mul_f32_e32 v142, v149, v155
	v_fma_f32 v144, v155, v149, -v142
	v_fmac_f32_e32 v144, v155, v150
	v_sub_f32_e32 v154, v143, v140
	v_add_f32_e32 v140, v142, v144
	v_sub_f32_e32 v143, v141, v140
	v_pk_add_f32 v[146:147], v[140:141], v[142:143] neg_lo:[0,1] neg_hi:[0,1]
	v_mov_b32_e32 v145, v140
	v_pk_add_f32 v[140:141], v[146:147], v[144:145] neg_lo:[0,1] neg_hi:[0,1]
	s_mov_b32 s31, 0x3f317218
	v_add_f32_e32 v141, v154, v141
	v_add_f32_e32 v140, v140, v141
	v_add_f32_e32 v141, v143, v140
	v_mul_f32_e32 v154, v151, v141
	v_mul_f32_e32 v142, v149, v154
	v_fma_f32 v144, v154, v149, -v142
	v_fmac_f32_e32 v144, v154, v150
	v_sub_f32_e32 v143, v143, v141
	v_add_f32_e32 v149, v140, v143
	v_add_f32_e32 v140, v142, v144
	v_sub_f32_e32 v143, v141, v140
	v_pk_add_f32 v[146:147], v[140:141], v[142:143] neg_lo:[0,1] neg_hi:[0,1]
	v_mov_b32_e32 v145, v140
	v_pk_add_f32 v[140:141], v[146:147], v[144:145] neg_lo:[0,1] neg_hi:[0,1]
	s_nop 0
	v_add_f32_e32 v141, v149, v141
	v_add_f32_e32 v140, v140, v141
	v_add_f32_e32 v141, v155, v154
	v_add_f32_e32 v140, v143, v140
	v_sub_f32_e32 v142, v141, v155
	v_mul_f32_e32 v140, v151, v140
	v_sub_f32_e32 v142, v154, v142
	v_add_f32_e32 v142, v142, v140
	v_add_f32_e32 v144, v141, v142
	v_mul_f32_e32 v145, v144, v144
	v_fmamk_f32 v140, v145, 0x3e9b6dac, v218
	v_fmaak_f32 v171, v145, v140, 0x3f2aaada
	v_cvt_f32_i32_e32 v140, v148
	v_sub_f32_e32 v141, v144, v141
	v_sub_f32_e32 v141, v142, v141
	v_ldexp_f32 v146, v141, 1
	v_mul_f32_e32 v141, v144, v145
	v_ldexp_f32 v143, v144, 1
	v_pk_mul_f32 v[144:145], v[140:141], v[170:171]
	s_nop 0
	v_fma_f32 v142, v140, s31, -v144
	v_fmac_f32_e32 v142, 0xb102e308, v140
	v_pk_add_f32 v[140:141], v[144:145], v[142:143]
	s_mov_b32 s31, 0x7f800000
	v_sub_f32_e32 v143, v141, v143
	v_sub_f32_e32 v143, v145, v143
	v_add_f32_e32 v147, v146, v143
	v_mov_b32_e32 v146, v144
	v_pk_add_f32 v[144:145], v[140:141], v[144:145] neg_lo:[0,1] neg_hi:[0,1]
	v_pk_add_f32 v[148:149], v[140:141], v[146:147]
	v_mov_b32_e32 v143, v140
	v_mov_b32_e32 v145, v149
	v_pk_add_f32 v[150:151], v[142:143], v[144:145] neg_lo:[0,1] neg_hi:[0,1]
	v_pk_add_f32 v[142:143], v[142:143], v[144:145]
	v_mov_b32_e32 v146, v147
	v_pk_add_f32 v[144:145], v[142:143], v[140:141] op_sel:[1,0] op_sel_hi:[0,1] neg_lo:[0,1] neg_hi:[0,1]
	v_pk_add_f32 v[154:155], v[148:149], v[144:145] op_sel_hi:[1,0] neg_lo:[0,1] neg_hi:[0,1]
	v_mov_b32_e32 v148, v149
	v_mov_b32_e32 v149, v143
	v_pk_mov_b32 v[144:145], v[140:141], v[144:145] op_sel:[1,0]
	v_mov_b32_e32 v147, v140
	v_pk_add_f32 v[144:145], v[148:149], v[144:145] neg_lo:[0,1] neg_hi:[0,1]
	v_mov_b32_e32 v154, v150
	v_pk_add_f32 v[140:141], v[146:147], v[144:145] neg_lo:[0,1] neg_hi:[0,1]
	v_mov_b32_e32 v151, v143
	v_pk_add_f32 v[144:145], v[154:155], v[140:141]
	v_cmp_neq_f32_e32 vcc, s31, v156
	v_pk_add_f32 v[146:147], v[144:145], v[144:145] op_sel:[0,1] op_sel_hi:[1,0]
	s_mov_b32 s31, 0x33800000
	v_pk_add_f32 v[142:143], v[142:143], v[146:147] op_sel:[1,0] op_sel_hi:[0,1]
	v_mov_b32_e32 v145, v142
	v_pk_add_f32 v[148:149], v[144:145], v[150:151] neg_lo:[0,1] neg_hi:[0,1]
	v_mov_b32_e32 v141, v146
	v_sub_f32_e32 v143, v144, v148
	v_pk_add_f32 v[140:141], v[140:141], v[148:149] neg_lo:[0,1] neg_hi:[0,1]
	v_sub_f32_e32 v143, v150, v143
	v_add_f32_e32 v140, v140, v143
	v_add_f32_e32 v140, v140, v141
	v_add_f32_e32 v140, v142, v140
	v_cndmask_b32_e32 v140, v214, v140, vcc
	v_cmp_ngt_f32_e32 vcc, -1.0, v156
	s_nop 1
	v_cndmask_b32_e32 v140, v215, v140, vcc
	v_cmp_neq_f32_e32 vcc, -1.0, v156
	s_nop 1
	v_cndmask_b32_e32 v140, v213, v140, vcc
	v_cmp_lt_f32_e64 vcc, |v156|, s31
	s_nop 1
	v_cndmask_b32_e32 v154, v140, v156, vcc
.LBB0_335:
	s_andn2_saveexec_b64 s[0:1], s[0:1]
	s_or_b64 exec, exec, s[0:1]
	s_mov_b32 s0, 0xc1700000
	v_cmp_ngt_f32_e32 vcc, s0, v234
	v_xor_b32_e32 v155, 0x80000000, v234
	s_and_saveexec_b64 s[0:1], vcc
	s_xor_b64 s[0:1], exec, s[0:1]
	s_cbranch_execz .LBB0_337
	v_mul_f32_e32 v140, 0xbfb8aa3b, v234
	v_exp_f32_e32 v155, v140
	s_mov_b32 s31, 0x3f2aaaab
	v_add_f32_e32 v142, 1.0, v155
	v_frexp_mant_f32_e32 v144, v142
	v_cvt_f64_f32_e32 v[140:141], v142
	v_frexp_exp_i32_f64_e32 v140, v[140:141]
	v_cmp_gt_f32_e32 vcc, s31, v144
	v_add_f32_e32 v143, -1.0, v142
	v_sub_f32_e32 v145, v143, v142
	v_subbrev_co_u32_e32 v148, vcc, 0, v140, vcc
	v_sub_u32_e32 v140, 0, v148
	v_sub_f32_e32 v143, v155, v143
	v_add_f32_e32 v145, 1.0, v145
	v_ldexp_f32 v141, v142, v140
	v_add_f32_e32 v143, v143, v145
	v_add_f32_e32 v142, -1.0, v141
	v_add_f32_e32 v144, 1.0, v141
	v_ldexp_f32 v140, v143, v140
	v_add_f32_e32 v143, 1.0, v142
	v_add_f32_e32 v145, -1.0, v144
	v_sub_f32_e32 v143, v141, v143
	v_sub_f32_e32 v141, v141, v145
	v_add_f32_e32 v143, v140, v143
	v_add_f32_e32 v140, v140, v141
	v_add_f32_e32 v149, v144, v140
	v_rcp_f32_e32 v151, v149
	v_sub_f32_e32 v141, v149, v144
	v_sub_f32_e32 v150, v140, v141
	v_add_f32_e32 v141, v142, v143
	v_mul_f32_e32 v157, v141, v151
	v_sub_f32_e32 v140, v141, v142
	v_mul_f32_e32 v142, v149, v157
	v_fma_f32 v144, v157, v149, -v142
	v_fmac_f32_e32 v144, v157, v150
	v_sub_f32_e32 v156, v143, v140
	v_add_f32_e32 v140, v142, v144
	v_sub_f32_e32 v143, v141, v140
	v_pk_add_f32 v[146:147], v[140:141], v[142:143] neg_lo:[0,1] neg_hi:[0,1]
	v_mov_b32_e32 v145, v140
	v_pk_add_f32 v[140:141], v[146:147], v[144:145] neg_lo:[0,1] neg_hi:[0,1]
	s_mov_b32 s31, 0x3f317218
	v_add_f32_e32 v141, v156, v141
	v_add_f32_e32 v140, v140, v141
	v_add_f32_e32 v141, v143, v140
	v_mul_f32_e32 v156, v151, v141
	v_mul_f32_e32 v142, v149, v156
	v_fma_f32 v144, v156, v149, -v142
	v_fmac_f32_e32 v144, v156, v150
	v_sub_f32_e32 v143, v143, v141
	v_add_f32_e32 v149, v140, v143
	v_add_f32_e32 v140, v142, v144
	v_sub_f32_e32 v143, v141, v140
	v_pk_add_f32 v[146:147], v[140:141], v[142:143] neg_lo:[0,1] neg_hi:[0,1]
	v_mov_b32_e32 v145, v140
	v_pk_add_f32 v[140:141], v[146:147], v[144:145] neg_lo:[0,1] neg_hi:[0,1]
	s_nop 0
	v_add_f32_e32 v141, v149, v141
	v_add_f32_e32 v140, v140, v141
	v_add_f32_e32 v141, v157, v156
	v_add_f32_e32 v140, v143, v140
	v_sub_f32_e32 v142, v141, v157
	v_mul_f32_e32 v140, v151, v140
	v_sub_f32_e32 v142, v156, v142
	v_add_f32_e32 v142, v142, v140
	v_add_f32_e32 v144, v141, v142
	v_mul_f32_e32 v145, v144, v144
	v_fmamk_f32 v140, v145, 0x3e9b6dac, v218
	v_fmaak_f32 v171, v145, v140, 0x3f2aaada
	v_cvt_f32_i32_e32 v140, v148
	v_sub_f32_e32 v141, v144, v141
	v_sub_f32_e32 v141, v142, v141
	v_ldexp_f32 v146, v141, 1
	v_mul_f32_e32 v141, v144, v145
	v_ldexp_f32 v143, v144, 1
	v_pk_mul_f32 v[144:145], v[140:141], v[170:171]
	s_nop 0
	v_fma_f32 v142, v140, s31, -v144
	v_fmac_f32_e32 v142, 0xb102e308, v140
	v_pk_add_f32 v[140:141], v[144:145], v[142:143]
	s_mov_b32 s31, 0x7f800000
	v_sub_f32_e32 v143, v141, v143
	v_sub_f32_e32 v143, v145, v143
	v_add_f32_e32 v147, v146, v143
	v_mov_b32_e32 v146, v144
	v_pk_add_f32 v[144:145], v[140:141], v[144:145] neg_lo:[0,1] neg_hi:[0,1]
	v_pk_add_f32 v[148:149], v[140:141], v[146:147]
	v_mov_b32_e32 v143, v140
	v_mov_b32_e32 v145, v149
	v_pk_add_f32 v[150:151], v[142:143], v[144:145] neg_lo:[0,1] neg_hi:[0,1]
	v_pk_add_f32 v[142:143], v[142:143], v[144:145]
	v_mov_b32_e32 v146, v147
	v_pk_add_f32 v[144:145], v[142:143], v[140:141] op_sel:[1,0] op_sel_hi:[0,1] neg_lo:[0,1] neg_hi:[0,1]
	v_pk_add_f32 v[156:157], v[148:149], v[144:145] op_sel_hi:[1,0] neg_lo:[0,1] neg_hi:[0,1]
	v_mov_b32_e32 v148, v149
	v_mov_b32_e32 v149, v143
	v_pk_mov_b32 v[144:145], v[140:141], v[144:145] op_sel:[1,0]
	v_mov_b32_e32 v147, v140
	v_pk_add_f32 v[144:145], v[148:149], v[144:145] neg_lo:[0,1] neg_hi:[0,1]
	v_mov_b32_e32 v156, v150
	v_pk_add_f32 v[140:141], v[146:147], v[144:145] neg_lo:[0,1] neg_hi:[0,1]
	v_mov_b32_e32 v151, v143
	v_pk_add_f32 v[144:145], v[156:157], v[140:141]
	v_cmp_neq_f32_e32 vcc, s31, v155
	v_pk_add_f32 v[146:147], v[144:145], v[144:145] op_sel:[0,1] op_sel_hi:[1,0]
	s_mov_b32 s31, 0x33800000
	v_pk_add_f32 v[142:143], v[142:143], v[146:147] op_sel:[1,0] op_sel_hi:[0,1]
	v_mov_b32_e32 v145, v142
	v_pk_add_f32 v[148:149], v[144:145], v[150:151] neg_lo:[0,1] neg_hi:[0,1]
	v_mov_b32_e32 v141, v146
	v_sub_f32_e32 v143, v144, v148
	v_pk_add_f32 v[140:141], v[140:141], v[148:149] neg_lo:[0,1] neg_hi:[0,1]
	v_sub_f32_e32 v143, v150, v143
	v_add_f32_e32 v140, v140, v143
	v_add_f32_e32 v140, v140, v141
	v_add_f32_e32 v140, v142, v140
	v_cndmask_b32_e32 v140, v214, v140, vcc
	v_cmp_ngt_f32_e32 vcc, -1.0, v155
	s_nop 1
	v_cndmask_b32_e32 v140, v215, v140, vcc
	v_cmp_neq_f32_e32 vcc, -1.0, v155
	s_nop 1
	v_cndmask_b32_e32 v140, v213, v140, vcc
	v_cmp_lt_f32_e64 vcc, |v155|, s31
	s_nop 1
	v_cndmask_b32_e32 v155, v140, v155, vcc
.LBB0_337:
	s_andn2_saveexec_b64 s[0:1], s[0:1]
	s_or_b64 exec, exec, s[0:1]
	s_mul_hi_i32 s31, s30, 0x1800000
	s_mul_i32 s30, s30, 0x1800000
	v_readlane_b32 s0, v251, 43
	v_readlane_b32 s1, v251, 44
	s_add_u32 s0, s0, s30
	s_addc_u32 s1, s1, s31
	v_readlane_b32 s42, v251, 45
	v_readlane_b32 s43, v251, 46
	s_add_u32 s30, s42, s30
	s_addc_u32 s31, s43, s31
	s_lshl_b32 s42, s75, 8
	s_add_i32 s42, s42, s72
	v_add_u32_e32 v140, s42, v139
	v_ashrrev_i32_e32 v139, 31, v138
	v_lshlrev_b64 v[142:143], 1, v[138:139]
	v_ashrrev_i32_e32 v141, 31, v140
	v_lshl_add_u64 v[150:151], s[22:23], 0, v[142:143]
	v_lshlrev_b64 v[162:163], 10, v[140:141]
	v_lshl_add_u64 v[138:139], v[150:151], 0, v[162:163]
	global_load_dwordx2 v[164:165], v[138:139], off
	v_add_f32_e32 v122, v122, v196
	v_mul_f32_e32 v122, 0xbfb8aa3b, v122
	v_add_f32_e32 v123, v123, v199
	v_exp_f32_e32 v146, v122
	v_add_u32_e32 v122, 16, v140
	v_mul_f32_e32 v144, 0xbfb8aa3b, v123
	v_ashrrev_i32_e32 v123, 31, v122
	v_add_f32_e32 v126, v126, v197
	v_add_f32_e32 v127, v127, v198
	v_lshlrev_b64 v[166:167], 10, v[122:123]
	v_mul_f32_e32 v141, 0xbfb8aa3b, v126
	v_mul_f32_e32 v145, 0xbfb8aa3b, v127
	v_lshl_add_u64 v[126:127], v[150:151], 0, v[166:167]
	global_load_dwordx2 v[168:169], v[126:127], off
	v_exp_f32_e32 v122, v141
	v_exp_f32_e32 v123, v144
	v_exp_f32_e32 v141, v145
	v_lshl_add_u64 v[158:159], s[0:1], 0, v[142:143]
	v_add_f32_e32 v145, 1.0, v122
	v_add_f32_e32 v123, 1.0, v123
	v_add_u32_e32 v122, 32, v140
	v_lshl_add_u64 v[156:157], s[30:31], 0, v[142:143]
	v_add_f32_e32 v143, 1.0, v146
	v_add_f32_e32 v141, 1.0, v141
	v_add_u32_e32 v142, 48, v140
	v_add_u32_e32 v144, 0x80, v140
	v_add_u32_e32 v146, 0x90, v140
	v_add_u32_e32 v148, 0xa0, v140
	v_add_u32_e32 v140, 0xb0, v140
	v_rcp_f32_e32 v173, v123
	v_ashrrev_i32_e32 v123, 31, v122
	v_rcp_f32_e32 v172, v143
	v_rcp_f32_e32 v171, v145
	v_rcp_f32_e32 v206, v141
	v_ashrrev_i32_e32 v143, 31, v142
	v_ashrrev_i32_e32 v145, 31, v144
	v_ashrrev_i32_e32 v147, 31, v146
	v_ashrrev_i32_e32 v149, 31, v148
	v_ashrrev_i32_e32 v141, 31, v140
	v_lshlrev_b64 v[208:209], 10, v[122:123]
	v_lshlrev_b64 v[188:189], 10, v[142:143]
	v_lshlrev_b64 v[184:185], 10, v[144:145]
	v_lshlrev_b64 v[180:181], 10, v[146:147]
	v_lshlrev_b64 v[176:177], 10, v[148:149]
	v_lshlrev_b64 v[160:161], 10, v[140:141]
	v_lshl_add_u64 v[140:141], v[150:151], 0, v[208:209]
	v_lshl_add_u64 v[142:143], v[150:151], 0, v[188:189]
	v_lshl_add_u64 v[144:145], v[150:151], 0, v[184:185]
	v_lshl_add_u64 v[146:147], v[150:151], 0, v[180:181]
	v_lshl_add_u64 v[148:149], v[150:151], 0, v[176:177]
	v_lshl_add_u64 v[150:151], v[150:151], 0, v[160:161]
	global_load_dwordx2 v[216:217], v[140:141], off
	global_load_dwordx2 v[190:191], v[142:143], off
	global_load_dwordx2 v[186:187], v[144:145], off
	global_load_dwordx2 v[182:183], v[146:147], off
	global_load_dwordx2 v[178:179], v[148:149], off
	global_load_dwordx2 v[174:175], v[150:151], off
	v_add_f32_e32 v128, v128, v200
	v_mul_f32_e32 v128, 0xbfb8aa3b, v128
	v_exp_f32_e32 v128, v128
	v_add_f32_e32 v124, v124, v201
	v_add_f32_e32 v125, v125, v203
	v_mul_f32_e32 v124, 0xbfb8aa3b, v124
	v_add_f32_e32 v128, 1.0, v128
	v_mul_f32_e32 v125, 0xbfb8aa3b, v125
	v_exp_f32_e32 v124, v124
	v_rcp_f32_e32 v207, v128
	v_exp_f32_e32 v125, v125
	v_add_f32_e32 v128, v129, v202
	v_pk_mul_f32 v[122:123], v[172:173], s[64:65] op_sel_hi:[1,0]
	v_mul_f32_e32 v128, 0xbfb8aa3b, v128
	v_pk_mul_f32 v[122:123], v[122:123], v[152:153]
	v_exp_f32_e32 v129, v128
	v_cvt_pk_f16_f32 v122, v122, v123
	v_add_f32_e32 v124, 1.0, v124
	v_add_f32_e32 v125, 1.0, v125
	v_add_f32_e32 v118, v118, v197
	v_rcp_f32_e32 v124, v124
	v_rcp_f32_e32 v125, v125
	v_mul_f32_e32 v118, 0xbfb8aa3b, v118
	v_exp_f32_e32 v118, v118
	v_add_f32_e32 v114, v114, v196
	v_add_f32_e32 v115, v115, v199
	v_pk_mul_f32 v[124:125], v[124:125], s[64:65] op_sel_hi:[1,0]
	s_waitcnt vmcnt(0)
	v_lshlrev_b32_e32 v123, 16, v164
	v_and_b32_e32 v172, 0xffff0000, v165
	v_and_b32_e32 v164, 0xffff0000, v164
	v_lshlrev_b32_e32 v165, 16, v165
	v_pk_mul_f32 v[164:165], v[206:207], v[164:165]
	v_fma_mixlo_f16 v123, v171, v123, 0
	v_cvt_pk_f16_f32 v164, v164, v165
	v_pack_b32_f16 v128, v123, v164
	v_add_f32_e32 v123, 1.0, v129
	v_rcp_f32_e32 v129, v123
	v_mul_f32_e32 v114, 0xbfb8aa3b, v114
	v_mul_f32_e32 v115, 0xbfb8aa3b, v115
	v_add_f32_e32 v119, v119, v198
	v_pk_mul_f32 v[124:125], v[124:125], v[154:155]
	v_exp_f32_e32 v114, v114
	v_add_f32_e32 v118, 1.0, v118
	v_exp_f32_e32 v115, v115
	v_mul_f32_e32 v119, 0xbfb8aa3b, v119
	v_cvt_pk_f16_f32 v123, v124, v125
	v_fma_mixlo_f16 v124, v129, v172, 0
	v_rcp_f32_e32 v118, v118
	v_exp_f32_e32 v119, v119
	v_alignbit_b32 v129, v124, v164, 16
	v_lshl_add_u64 v[124:125], v[158:159], 0, v[162:163]
	global_store_dwordx2 v[124:125], v[122:123], off
	v_lshl_add_u64 v[122:123], v[156:157], 0, v[162:163]
	v_add_f32_e32 v116, v116, v201
	global_store_dwordx2 v[122:123], v[128:129], off
	v_lshlrev_b32_e32 v128, 16, v168
	v_add_f32_e32 v114, 1.0, v114
	v_add_f32_e32 v115, 1.0, v115
	v_mul_f32_e32 v116, 0xbfb8aa3b, v116
	v_rcp_f32_e32 v114, v114
	v_rcp_f32_e32 v115, v115
	v_fma_mixlo_f16 v163, v118, v128, 0
	v_add_f32_e32 v118, 1.0, v119
	v_exp_f32_e32 v119, v116
	v_add_f32_e32 v116, v120, v200
	v_mul_f32_e32 v116, 0xbfb8aa3b, v116
	v_exp_f32_e32 v120, v116
	v_pk_mul_f32 v[114:115], v[114:115], s[64:65] op_sel_hi:[1,0]
	v_add_f32_e32 v110, v110, v197
	v_pk_mul_f32 v[114:115], v[114:115], v[152:153]
	v_mul_f32_e32 v110, 0xbfb8aa3b, v110
	v_cvt_pk_f16_f32 v116, v114, v115
	v_add_f32_e32 v115, 1.0, v120
	v_add_f32_e32 v114, 1.0, v119
	v_rcp_f32_e32 v119, v115
	v_add_f32_e32 v115, v117, v203
	v_mul_f32_e32 v115, 0xbfb8aa3b, v115
	v_exp_f32_e32 v115, v115
	v_add_f32_e32 v117, v121, v202
	v_mul_f32_e32 v117, 0xbfb8aa3b, v117
	v_exp_f32_e32 v117, v117
	v_add_f32_e32 v115, 1.0, v115
	v_rcp_f32_e32 v114, v114
	v_rcp_f32_e32 v115, v115
	v_rcp_f32_e32 v118, v118
	v_add_f32_e32 v117, 1.0, v117
	v_exp_f32_e32 v110, v110
	v_rcp_f32_e32 v120, v117
	v_add_f32_e32 v106, v106, v196
	v_add_f32_e32 v107, v107, v199
	v_and_b32_e32 v128, 0xffff0000, v168
	v_lshlrev_b32_e32 v129, 16, v169
	v_pk_mul_f32 v[114:115], v[114:115], s[64:65] op_sel_hi:[1,0]
	v_mul_f32_e32 v106, 0xbfb8aa3b, v106
	v_mul_f32_e32 v107, 0xbfb8aa3b, v107
	v_add_f32_e32 v111, v111, v198
	v_and_b32_e32 v162, 0xffff0000, v169
	v_pk_mul_f32 v[118:119], v[118:119], v[128:129]
	v_pk_mul_f32 v[114:115], v[114:115], v[154:155]
	v_exp_f32_e32 v106, v106
	v_add_f32_e32 v110, 1.0, v110
	v_exp_f32_e32 v107, v107
	v_mul_f32_e32 v111, 0xbfb8aa3b, v111
	v_cvt_pk_f16_f32 v119, v118, v119
	v_cvt_pk_f16_f32 v117, v114, v115
	v_fma_mixlo_f16 v114, v120, v162, 0
	v_rcp_f32_e32 v110, v110
	v_exp_f32_e32 v111, v111
	v_pack_b32_f16 v118, v163, v119
	v_alignbit_b32 v119, v114, v119, 16
	v_lshl_add_u64 v[114:115], v[158:159], 0, v[166:167]
	global_store_dwordx2 v[114:115], v[116:117], off
	v_lshl_add_u64 v[116:117], v[156:157], 0, v[166:167]
	v_add_f32_e32 v108, v108, v201
	global_store_dwordx2 v[116:117], v[118:119], off
	v_lshlrev_b32_e32 v118, 16, v216
	v_add_f32_e32 v106, 1.0, v106
	v_add_f32_e32 v107, 1.0, v107
	v_mul_f32_e32 v108, 0xbfb8aa3b, v108
	v_rcp_f32_e32 v106, v106
	v_rcp_f32_e32 v107, v107
	v_fma_mixlo_f16 v121, v110, v118, 0
	v_add_f32_e32 v110, 1.0, v111
	v_exp_f32_e32 v111, v108
	v_add_f32_e32 v108, v112, v200
	v_mul_f32_e32 v108, 0xbfb8aa3b, v108
	v_exp_f32_e32 v112, v108
	v_pk_mul_f32 v[106:107], v[106:107], s[64:65] op_sel_hi:[1,0]
	v_add_f32_e32 v102, v102, v197
	v_pk_mul_f32 v[106:107], v[106:107], v[152:153]
	v_mul_f32_e32 v102, 0xbfb8aa3b, v102
	v_cvt_pk_f16_f32 v108, v106, v107
	v_add_f32_e32 v107, 1.0, v112
	v_add_f32_e32 v106, 1.0, v111
	v_rcp_f32_e32 v111, v107
	v_add_f32_e32 v107, v109, v203
	v_mul_f32_e32 v107, 0xbfb8aa3b, v107
	v_exp_f32_e32 v107, v107
	v_add_f32_e32 v109, v113, v202
	v_mul_f32_e32 v109, 0xbfb8aa3b, v109
	v_exp_f32_e32 v109, v109
	v_add_f32_e32 v107, 1.0, v107
	v_rcp_f32_e32 v106, v106
	v_rcp_f32_e32 v107, v107
	v_rcp_f32_e32 v110, v110
	v_add_f32_e32 v109, 1.0, v109
	v_exp_f32_e32 v102, v102
	v_rcp_f32_e32 v112, v109
	v_add_f32_e32 v92, v92, v196
	v_add_f32_e32 v93, v93, v199
	v_and_b32_e32 v118, 0xffff0000, v216
	v_lshlrev_b32_e32 v119, 16, v217
	v_pk_mul_f32 v[106:107], v[106:107], s[64:65] op_sel_hi:[1,0]
	v_mul_f32_e32 v92, 0xbfb8aa3b, v92
	v_mul_f32_e32 v93, 0xbfb8aa3b, v93
	v_add_f32_e32 v103, v103, v198
	v_and_b32_e32 v120, 0xffff0000, v217
	v_pk_mul_f32 v[110:111], v[110:111], v[118:119]
	v_pk_mul_f32 v[106:107], v[106:107], v[154:155]
	v_exp_f32_e32 v92, v92
	v_add_f32_e32 v102, 1.0, v102
	v_exp_f32_e32 v93, v93
	v_mul_f32_e32 v103, 0xbfb8aa3b, v103
	v_cvt_pk_f16_f32 v111, v110, v111
	v_cvt_pk_f16_f32 v109, v106, v107
	v_fma_mixlo_f16 v106, v112, v120, 0
	v_rcp_f32_e32 v102, v102
	v_exp_f32_e32 v103, v103
	v_pack_b32_f16 v110, v121, v111
	v_alignbit_b32 v111, v106, v111, 16
	v_lshl_add_u64 v[106:107], v[158:159], 0, v[208:209]
	global_store_dwordx2 v[106:107], v[108:109], off
	v_lshl_add_u64 v[108:109], v[156:157], 0, v[208:209]
	v_add_f32_e32 v94, v94, v201
	global_store_dwordx2 v[108:109], v[110:111], off
	v_lshlrev_b32_e32 v110, 16, v190
	v_add_f32_e32 v92, 1.0, v92
	v_add_f32_e32 v93, 1.0, v93
	v_mul_f32_e32 v94, 0xbfb8aa3b, v94
	v_rcp_f32_e32 v92, v92
	v_rcp_f32_e32 v93, v93
	v_fma_mixlo_f16 v113, v102, v110, 0
	v_add_f32_e32 v102, 1.0, v103
	v_exp_f32_e32 v103, v94
	v_add_f32_e32 v94, v104, v200
	v_mul_f32_e32 v94, 0xbfb8aa3b, v94
	v_exp_f32_e32 v104, v94
	v_pk_mul_f32 v[92:93], v[92:93], s[64:65] op_sel_hi:[1,0]
	v_add_f32_e32 v98, v98, v197
	v_pk_mul_f32 v[92:93], v[92:93], v[152:153]
	v_mul_f32_e32 v98, 0xbfb8aa3b, v98
	v_cvt_pk_f16_f32 v94, v92, v93
	v_add_f32_e32 v93, 1.0, v104
	v_add_f32_e32 v92, 1.0, v103
	v_rcp_f32_e32 v103, v93
	v_add_f32_e32 v93, v95, v203
	v_mul_f32_e32 v93, 0xbfb8aa3b, v93
	v_exp_f32_e32 v93, v93
	v_add_f32_e32 v95, v105, v202
	v_mul_f32_e32 v95, 0xbfb8aa3b, v95
	v_exp_f32_e32 v95, v95
	v_add_f32_e32 v93, 1.0, v93
	v_rcp_f32_e32 v92, v92
	v_rcp_f32_e32 v93, v93
	v_rcp_f32_e32 v102, v102
	v_add_f32_e32 v95, 1.0, v95
	v_exp_f32_e32 v98, v98
	v_rcp_f32_e32 v104, v95
	v_add_f32_e32 v88, v88, v196
	v_add_f32_e32 v89, v89, v199
	v_and_b32_e32 v110, 0xffff0000, v190
	v_lshlrev_b32_e32 v111, 16, v191
	v_pk_mul_f32 v[92:93], v[92:93], s[64:65] op_sel_hi:[1,0]
	v_mul_f32_e32 v88, 0xbfb8aa3b, v88
	v_mul_f32_e32 v89, 0xbfb8aa3b, v89
	v_add_f32_e32 v99, v99, v198
	v_and_b32_e32 v112, 0xffff0000, v191
	v_pk_mul_f32 v[102:103], v[102:103], v[110:111]
	v_pk_mul_f32 v[92:93], v[92:93], v[154:155]
	v_exp_f32_e32 v88, v88
	v_add_f32_e32 v98, 1.0, v98
	v_exp_f32_e32 v89, v89
	v_mul_f32_e32 v99, 0xbfb8aa3b, v99
	v_cvt_pk_f16_f32 v103, v102, v103
	v_cvt_pk_f16_f32 v95, v92, v93
	v_fma_mixlo_f16 v92, v104, v112, 0
	v_rcp_f32_e32 v98, v98
	v_exp_f32_e32 v99, v99
	v_pack_b32_f16 v102, v113, v103
	v_alignbit_b32 v103, v92, v103, 16
	v_lshl_add_u64 v[92:93], v[158:159], 0, v[188:189]
	global_store_dwordx2 v[92:93], v[94:95], off
	v_lshl_add_u64 v[94:95], v[156:157], 0, v[188:189]
	v_add_f32_e32 v90, v90, v201
	global_store_dwordx2 v[94:95], v[102:103], off
	v_lshlrev_b32_e32 v102, 16, v186
	v_add_f32_e32 v88, 1.0, v88
	v_add_f32_e32 v89, 1.0, v89
	v_mul_f32_e32 v90, 0xbfb8aa3b, v90
	v_rcp_f32_e32 v88, v88
	v_rcp_f32_e32 v89, v89
	v_fma_mixlo_f16 v105, v98, v102, 0
	v_add_f32_e32 v98, 1.0, v99
	v_exp_f32_e32 v99, v90
	v_add_f32_e32 v90, v100, v200
	v_mul_f32_e32 v90, 0xbfb8aa3b, v90
	v_exp_f32_e32 v100, v90
	v_pk_mul_f32 v[88:89], v[88:89], s[64:65] op_sel_hi:[1,0]
	v_add_f32_e32 v84, v84, v197
	v_pk_mul_f32 v[88:89], v[88:89], v[152:153]
	v_mul_f32_e32 v84, 0xbfb8aa3b, v84
	v_cvt_pk_f16_f32 v90, v88, v89
	v_add_f32_e32 v89, 1.0, v100
	v_add_f32_e32 v88, 1.0, v99
	v_rcp_f32_e32 v99, v89
	v_add_f32_e32 v89, v91, v203
	v_mul_f32_e32 v89, 0xbfb8aa3b, v89
	v_exp_f32_e32 v89, v89
	v_add_f32_e32 v91, v101, v202
	v_mul_f32_e32 v91, 0xbfb8aa3b, v91
	v_exp_f32_e32 v91, v91
	v_add_f32_e32 v89, 1.0, v89
	v_rcp_f32_e32 v88, v88
	v_rcp_f32_e32 v89, v89
	v_rcp_f32_e32 v98, v98
	v_add_f32_e32 v91, 1.0, v91
	v_exp_f32_e32 v84, v84
	v_rcp_f32_e32 v100, v91
	v_add_f32_e32 v80, v80, v196
	v_add_f32_e32 v81, v81, v199
	v_and_b32_e32 v102, 0xffff0000, v186
	v_lshlrev_b32_e32 v103, 16, v187
	v_pk_mul_f32 v[88:89], v[88:89], s[64:65] op_sel_hi:[1,0]
	v_mul_f32_e32 v80, 0xbfb8aa3b, v80
	v_mul_f32_e32 v81, 0xbfb8aa3b, v81
	v_add_f32_e32 v85, v85, v198
	v_and_b32_e32 v104, 0xffff0000, v187
	v_pk_mul_f32 v[98:99], v[98:99], v[102:103]
	v_pk_mul_f32 v[88:89], v[88:89], v[154:155]
	v_exp_f32_e32 v80, v80
	v_add_f32_e32 v84, 1.0, v84
	v_exp_f32_e32 v81, v81
	v_mul_f32_e32 v85, 0xbfb8aa3b, v85
	v_cvt_pk_f16_f32 v99, v98, v99
	v_cvt_pk_f16_f32 v91, v88, v89
	v_fma_mixlo_f16 v88, v100, v104, 0
	v_rcp_f32_e32 v84, v84
	v_exp_f32_e32 v85, v85
	v_pack_b32_f16 v98, v105, v99
	v_alignbit_b32 v99, v88, v99, 16
	v_lshl_add_u64 v[88:89], v[158:159], 0, v[184:185]
	global_store_dwordx2 v[88:89], v[90:91], off
	v_lshl_add_u64 v[90:91], v[156:157], 0, v[184:185]
	v_add_f32_e32 v82, v82, v201
	global_store_dwordx2 v[90:91], v[98:99], off
	v_lshlrev_b32_e32 v98, 16, v182
	v_add_f32_e32 v80, 1.0, v80
	v_add_f32_e32 v81, 1.0, v81
	v_mul_f32_e32 v82, 0xbfb8aa3b, v82
	v_rcp_f32_e32 v80, v80
	v_rcp_f32_e32 v81, v81
	v_fma_mixlo_f16 v101, v84, v98, 0
	v_add_f32_e32 v84, 1.0, v85
	v_exp_f32_e32 v85, v82
	v_add_f32_e32 v82, v86, v200
	v_mul_f32_e32 v82, 0xbfb8aa3b, v82
	v_exp_f32_e32 v86, v82
	v_pk_mul_f32 v[80:81], v[80:81], s[64:65] op_sel_hi:[1,0]
	v_add_f32_e32 v76, v76, v197
	v_pk_mul_f32 v[80:81], v[80:81], v[152:153]
	v_mul_f32_e32 v76, 0xbfb8aa3b, v76
	v_cvt_pk_f16_f32 v82, v80, v81
	v_add_f32_e32 v81, 1.0, v86
	v_add_f32_e32 v80, 1.0, v85
	v_rcp_f32_e32 v85, v81
	v_add_f32_e32 v81, v83, v203
	v_mul_f32_e32 v81, 0xbfb8aa3b, v81
	v_exp_f32_e32 v81, v81
	v_add_f32_e32 v83, v87, v202
	v_mul_f32_e32 v83, 0xbfb8aa3b, v83
	v_exp_f32_e32 v83, v83
	v_add_f32_e32 v81, 1.0, v81
	v_rcp_f32_e32 v80, v80
	v_rcp_f32_e32 v81, v81
	v_rcp_f32_e32 v84, v84
	v_add_f32_e32 v83, 1.0, v83
	v_exp_f32_e32 v76, v76
	v_rcp_f32_e32 v86, v83
	v_add_f32_e32 v72, v72, v196
	v_add_f32_e32 v73, v73, v199
	v_and_b32_e32 v98, 0xffff0000, v182
	v_lshlrev_b32_e32 v99, 16, v183
	v_pk_mul_f32 v[80:81], v[80:81], s[64:65] op_sel_hi:[1,0]
	v_mul_f32_e32 v72, 0xbfb8aa3b, v72
	v_mul_f32_e32 v73, 0xbfb8aa3b, v73
	v_add_f32_e32 v77, v77, v198
	v_and_b32_e32 v100, 0xffff0000, v183
	v_pk_mul_f32 v[84:85], v[84:85], v[98:99]
	v_pk_mul_f32 v[80:81], v[80:81], v[154:155]
	v_exp_f32_e32 v72, v72
	v_add_f32_e32 v76, 1.0, v76
	v_exp_f32_e32 v73, v73
	v_mul_f32_e32 v77, 0xbfb8aa3b, v77
	v_cvt_pk_f16_f32 v85, v84, v85
	v_cvt_pk_f16_f32 v83, v80, v81
	v_fma_mixlo_f16 v80, v86, v100, 0
	v_rcp_f32_e32 v76, v76
	v_exp_f32_e32 v77, v77
	v_pack_b32_f16 v84, v101, v85
	v_alignbit_b32 v85, v80, v85, 16
	v_lshl_add_u64 v[80:81], v[158:159], 0, v[180:181]
	global_store_dwordx2 v[80:81], v[82:83], off
	v_lshl_add_u64 v[82:83], v[156:157], 0, v[180:181]
	v_add_f32_e32 v74, v74, v201
	global_store_dwordx2 v[82:83], v[84:85], off
	v_lshlrev_b32_e32 v84, 16, v178
	v_add_f32_e32 v72, 1.0, v72
	v_add_f32_e32 v73, 1.0, v73
	v_mul_f32_e32 v74, 0xbfb8aa3b, v74
	v_rcp_f32_e32 v72, v72
	v_rcp_f32_e32 v73, v73
	v_fma_mixlo_f16 v87, v76, v84, 0
	v_add_f32_e32 v76, 1.0, v77
	v_exp_f32_e32 v77, v74
	v_add_f32_e32 v74, v78, v200
	v_mul_f32_e32 v74, 0xbfb8aa3b, v74
	v_exp_f32_e32 v78, v74
	v_pk_mul_f32 v[72:73], v[72:73], s[64:65] op_sel_hi:[1,0]
	v_add_f32_e32 v68, v68, v197
	v_pk_mul_f32 v[72:73], v[72:73], v[152:153]
	v_mul_f32_e32 v68, 0xbfb8aa3b, v68
	v_cvt_pk_f16_f32 v74, v72, v73
	v_add_f32_e32 v73, 1.0, v78
	v_add_f32_e32 v72, 1.0, v77
	v_rcp_f32_e32 v77, v73
	v_add_f32_e32 v73, v75, v203
	v_mul_f32_e32 v73, 0xbfb8aa3b, v73
	v_exp_f32_e32 v73, v73
	v_add_f32_e32 v75, v79, v202
	v_mul_f32_e32 v75, 0xbfb8aa3b, v75
	v_exp_f32_e32 v75, v75
	v_add_f32_e32 v73, 1.0, v73
	v_rcp_f32_e32 v72, v72
	v_rcp_f32_e32 v73, v73
	v_rcp_f32_e32 v76, v76
	v_add_f32_e32 v75, 1.0, v75
	v_exp_f32_e32 v68, v68
	v_rcp_f32_e32 v78, v75
	v_add_f32_e32 v64, v64, v196
	v_add_f32_e32 v65, v65, v199
	v_and_b32_e32 v84, 0xffff0000, v178
	v_lshlrev_b32_e32 v85, 16, v179
	v_pk_mul_f32 v[72:73], v[72:73], s[64:65] op_sel_hi:[1,0]
	v_mul_f32_e32 v64, 0xbfb8aa3b, v64
	v_mul_f32_e32 v65, 0xbfb8aa3b, v65
	v_add_f32_e32 v69, v69, v198
	v_and_b32_e32 v86, 0xffff0000, v179
	v_pk_mul_f32 v[76:77], v[76:77], v[84:85]
	v_pk_mul_f32 v[72:73], v[72:73], v[154:155]
	v_exp_f32_e32 v64, v64
	v_add_f32_e32 v68, 1.0, v68
	v_exp_f32_e32 v65, v65
	v_mul_f32_e32 v69, 0xbfb8aa3b, v69
	v_cvt_pk_f16_f32 v77, v76, v77
	v_cvt_pk_f16_f32 v75, v72, v73
	v_fma_mixlo_f16 v72, v78, v86, 0
	v_rcp_f32_e32 v68, v68
	v_exp_f32_e32 v69, v69
	v_pack_b32_f16 v76, v87, v77
	v_alignbit_b32 v77, v72, v77, 16
	v_lshl_add_u64 v[72:73], v[158:159], 0, v[176:177]
	global_store_dwordx2 v[72:73], v[74:75], off
	v_lshl_add_u64 v[74:75], v[156:157], 0, v[176:177]
	v_add_f32_e32 v66, v66, v201
	global_store_dwordx2 v[74:75], v[76:77], off
	v_lshlrev_b32_e32 v76, 16, v174
	v_add_f32_e32 v64, 1.0, v64
	v_add_f32_e32 v65, 1.0, v65
	v_mul_f32_e32 v66, 0xbfb8aa3b, v66
	v_rcp_f32_e32 v64, v64
	v_rcp_f32_e32 v65, v65
	v_fma_mixlo_f16 v79, v68, v76, 0
	v_add_f32_e32 v68, 1.0, v69
	v_exp_f32_e32 v69, v66
	v_add_f32_e32 v66, v70, v200
	v_mul_f32_e32 v66, 0xbfb8aa3b, v66
	v_exp_f32_e32 v70, v66
	v_pk_mul_f32 v[64:65], v[64:65], s[64:65] op_sel_hi:[1,0]
	v_rcp_f32_e32 v68, v68
	v_pk_mul_f32 v[64:65], v[64:65], v[152:153]
	v_and_b32_e32 v76, 0xffff0000, v174
	v_cvt_pk_f16_f32 v66, v64, v65
	v_add_f32_e32 v65, 1.0, v70
	v_add_f32_e32 v64, 1.0, v69
	v_rcp_f32_e32 v69, v65
	v_add_f32_e32 v65, v67, v203
	v_mul_f32_e32 v65, 0xbfb8aa3b, v65
	v_exp_f32_e32 v65, v65
	v_add_f32_e32 v67, v71, v202
	v_mul_f32_e32 v67, 0xbfb8aa3b, v67
	v_exp_f32_e32 v67, v67
	v_add_f32_e32 v65, 1.0, v65
	v_rcp_f32_e32 v64, v64
	v_rcp_f32_e32 v65, v65
	v_add_f32_e32 v67, 1.0, v67
	v_rcp_f32_e32 v70, v67
	v_lshlrev_b32_e32 v77, 16, v175
	v_pk_mul_f32 v[64:65], v[64:65], s[64:65] op_sel_hi:[1,0]
	v_and_b32_e32 v78, 0xffff0000, v175
	v_pk_mul_f32 v[68:69], v[68:69], v[76:77]
	v_pk_mul_f32 v[64:65], v[64:65], v[154:155]
	v_cvt_pk_f16_f32 v69, v68, v69
	v_cvt_pk_f16_f32 v67, v64, v65
	v_fma_mixlo_f16 v64, v70, v78, 0
	v_pack_b32_f16 v68, v79, v69
	v_alignbit_b32 v69, v64, v69, 16
	v_lshl_add_u64 v[64:65], v[158:159], 0, v[160:161]
	global_store_dwordx2 v[64:65], v[66:67], off
	v_lshl_add_u64 v[66:67], v[156:157], 0, v[160:161]
	global_store_dwordx2 v[66:67], v[68:69], off
	global_load_dword v69, v[134:135], off offset:64
	s_nop 0
	global_load_dword v103, v[132:133], off offset:64
	global_load_dword v102, v[136:137], off offset:64
	global_load_dword v235, v[134:135], off offset:68
	global_load_dword v105, v[132:133], off offset:68
	global_load_dword v104, v[136:137], off offset:68
	global_load_dword v236, v[134:135], off offset:72
	global_load_dword v111, v[132:133], off offset:72
	global_load_dword v110, v[136:137], off offset:72
	global_load_dword v237, v[134:135], off offset:76
	global_load_dword v113, v[132:133], off offset:76
	global_load_dword v238, v[136:137], off offset:76
	s_mov_b32 s0, 0xc1700000
	s_waitcnt vmcnt(0)
	v_cmp_ngt_f32_e32 vcc, s0, v69
	v_xor_b32_e32 v68, 0x80000000, v69
	s_and_saveexec_b64 s[0:1], vcc
	s_xor_b64 s[0:1], exec, s[0:1]
	s_cbranch_execz .LBB0_339
	v_mul_f32_e32 v68, 0xbfb8aa3b, v69
	v_exp_f32_e32 v100, v68
	s_mov_b32 s30, 0x3f2aaaab
	v_add_f32_e32 v70, 1.0, v100
	v_frexp_mant_f32_e32 v76, v70
	v_cvt_f64_f32_e32 v[68:69], v70
	v_frexp_exp_i32_f64_e32 v68, v[68:69]
	v_cmp_gt_f32_e32 vcc, s30, v76
	v_add_f32_e32 v71, -1.0, v70
	v_sub_f32_e32 v77, v71, v70
	v_subbrev_co_u32_e32 v84, vcc, 0, v68, vcc
	v_sub_u32_e32 v68, 0, v84
	v_sub_f32_e32 v71, v100, v71
	v_add_f32_e32 v77, 1.0, v77
	v_ldexp_f32 v69, v70, v68
	v_add_f32_e32 v71, v71, v77
	v_add_f32_e32 v70, -1.0, v69
	v_add_f32_e32 v76, 1.0, v69
	v_ldexp_f32 v68, v71, v68
	v_add_f32_e32 v71, 1.0, v70
	v_add_f32_e32 v77, -1.0, v76
	v_sub_f32_e32 v71, v69, v71
	v_sub_f32_e32 v69, v69, v77
	v_add_f32_e32 v71, v68, v71
	v_add_f32_e32 v68, v68, v69
	v_add_f32_e32 v85, v76, v68
	v_rcp_f32_e32 v87, v85
	v_sub_f32_e32 v69, v85, v76
	v_sub_f32_e32 v86, v68, v69
	v_add_f32_e32 v69, v70, v71
	v_mul_f32_e32 v99, v69, v87
	v_sub_f32_e32 v68, v69, v70
	v_mul_f32_e32 v70, v85, v99
	v_fma_f32 v76, v99, v85, -v70
	v_fmac_f32_e32 v76, v99, v86
	v_sub_f32_e32 v98, v71, v68
	v_add_f32_e32 v68, v70, v76
	v_sub_f32_e32 v71, v69, v68
	v_pk_add_f32 v[78:79], v[68:69], v[70:71] neg_lo:[0,1] neg_hi:[0,1]
	v_mov_b32_e32 v77, v68
	v_pk_add_f32 v[68:69], v[78:79], v[76:77] neg_lo:[0,1] neg_hi:[0,1]
	s_mov_b32 s30, 0x3f317218
	v_add_f32_e32 v69, v98, v69
	v_add_f32_e32 v68, v68, v69
	v_add_f32_e32 v69, v71, v68
	v_mul_f32_e32 v98, v87, v69
	v_mul_f32_e32 v70, v85, v98
	v_fma_f32 v76, v98, v85, -v70
	v_fmac_f32_e32 v76, v98, v86
	v_sub_f32_e32 v71, v71, v69
	v_add_f32_e32 v85, v68, v71
	v_add_f32_e32 v68, v70, v76
	v_sub_f32_e32 v71, v69, v68
	v_pk_add_f32 v[78:79], v[68:69], v[70:71] neg_lo:[0,1] neg_hi:[0,1]
	v_mov_b32_e32 v77, v68
	v_pk_add_f32 v[68:69], v[78:79], v[76:77] neg_lo:[0,1] neg_hi:[0,1]
	s_nop 0
	v_add_f32_e32 v69, v85, v69
	v_add_f32_e32 v68, v68, v69
	v_add_f32_e32 v69, v99, v98
	v_add_f32_e32 v68, v71, v68
	v_sub_f32_e32 v70, v69, v99
	v_mul_f32_e32 v68, v87, v68
	v_sub_f32_e32 v70, v98, v70
	v_add_f32_e32 v70, v70, v68
	v_add_f32_e32 v76, v69, v70
	v_mul_f32_e32 v77, v76, v76
	v_fmamk_f32 v68, v77, 0x3e9b6dac, v218
	v_fmaak_f32 v171, v77, v68, 0x3f2aaada
	v_cvt_f32_i32_e32 v68, v84
	v_sub_f32_e32 v69, v76, v69
	v_sub_f32_e32 v69, v70, v69
	v_ldexp_f32 v78, v69, 1
	v_mul_f32_e32 v69, v76, v77
	v_ldexp_f32 v71, v76, 1
	v_pk_mul_f32 v[76:77], v[68:69], v[170:171]
	s_nop 0
	v_fma_f32 v70, v68, s30, -v76
	v_fmac_f32_e32 v70, 0xb102e308, v68
	v_pk_add_f32 v[68:69], v[76:77], v[70:71]
	s_mov_b32 s30, 0x7f800000
	v_sub_f32_e32 v71, v69, v71
	v_sub_f32_e32 v71, v77, v71
	v_add_f32_e32 v79, v78, v71
	v_mov_b32_e32 v78, v76
	v_pk_add_f32 v[76:77], v[68:69], v[76:77] neg_lo:[0,1] neg_hi:[0,1]
	v_pk_add_f32 v[84:85], v[68:69], v[78:79]
	v_mov_b32_e32 v71, v68
	v_mov_b32_e32 v77, v85
	v_pk_add_f32 v[86:87], v[70:71], v[76:77] neg_lo:[0,1] neg_hi:[0,1]
	v_pk_add_f32 v[70:71], v[70:71], v[76:77]
	v_mov_b32_e32 v78, v79
	v_pk_add_f32 v[76:77], v[70:71], v[68:69] op_sel:[1,0] op_sel_hi:[0,1] neg_lo:[0,1] neg_hi:[0,1]
	v_pk_add_f32 v[98:99], v[84:85], v[76:77] op_sel_hi:[1,0] neg_lo:[0,1] neg_hi:[0,1]
	v_mov_b32_e32 v84, v85
	v_mov_b32_e32 v85, v71
	v_pk_mov_b32 v[76:77], v[68:69], v[76:77] op_sel:[1,0]
	v_mov_b32_e32 v79, v68
	v_pk_add_f32 v[76:77], v[84:85], v[76:77] neg_lo:[0,1] neg_hi:[0,1]
	v_mov_b32_e32 v98, v86
	v_pk_add_f32 v[68:69], v[78:79], v[76:77] neg_lo:[0,1] neg_hi:[0,1]
	v_mov_b32_e32 v87, v71
	v_pk_add_f32 v[76:77], v[98:99], v[68:69]
	v_cmp_neq_f32_e32 vcc, s30, v100
	v_pk_add_f32 v[78:79], v[76:77], v[76:77] op_sel:[0,1] op_sel_hi:[1,0]
	s_mov_b32 s30, 0x33800000
	v_pk_add_f32 v[70:71], v[70:71], v[78:79] op_sel:[1,0] op_sel_hi:[0,1]
	v_mov_b32_e32 v77, v70
	v_pk_add_f32 v[84:85], v[76:77], v[86:87] neg_lo:[0,1] neg_hi:[0,1]
	v_mov_b32_e32 v69, v78
	v_sub_f32_e32 v71, v76, v84
	v_pk_add_f32 v[68:69], v[68:69], v[84:85] neg_lo:[0,1] neg_hi:[0,1]
	v_sub_f32_e32 v71, v86, v71
	v_add_f32_e32 v68, v68, v71
	v_add_f32_e32 v68, v68, v69
	v_add_f32_e32 v68, v70, v68
	v_cndmask_b32_e32 v68, v214, v68, vcc
	v_cmp_ngt_f32_e32 vcc, -1.0, v100
	s_nop 1
	v_cndmask_b32_e32 v68, v215, v68, vcc
	v_cmp_neq_f32_e32 vcc, -1.0, v100
	s_nop 1
	v_cndmask_b32_e32 v68, v213, v68, vcc
	v_cmp_lt_f32_e64 vcc, |v100|, s30
	s_nop 1
	v_cndmask_b32_e32 v68, v68, v100, vcc
.LBB0_339:
	s_andn2_saveexec_b64 s[0:1], s[0:1]
	s_or_b64 exec, exec, s[0:1]
	s_mov_b32 s0, 0xc1700000
	v_cmp_ngt_f32_e32 vcc, s0, v235
	v_xor_b32_e32 v69, 0x80000000, v235
	s_and_saveexec_b64 s[0:1], vcc
	s_xor_b64 s[0:1], exec, s[0:1]
	s_cbranch_execz .LBB0_341
	v_mul_f32_e32 v69, 0xbfb8aa3b, v235
	v_exp_f32_e32 v69, v69
	s_mov_b32 s30, 0x3f2aaaab
	v_add_f32_e32 v76, 1.0, v69
	v_frexp_mant_f32_e32 v78, v76
	v_cvt_f64_f32_e32 v[70:71], v76
	v_frexp_exp_i32_f64_e32 v70, v[70:71]
	v_cmp_gt_f32_e32 vcc, s30, v78
	v_add_f32_e32 v77, -1.0, v76
	v_sub_f32_e32 v79, v77, v76
	v_subbrev_co_u32_e32 v86, vcc, 0, v70, vcc
	v_sub_u32_e32 v70, 0, v86
	v_sub_f32_e32 v77, v69, v77
	v_add_f32_e32 v79, 1.0, v79
	v_ldexp_f32 v71, v76, v70
	v_add_f32_e32 v77, v77, v79
	v_add_f32_e32 v76, -1.0, v71
	v_add_f32_e32 v78, 1.0, v71
	v_ldexp_f32 v70, v77, v70
	v_add_f32_e32 v77, 1.0, v76
	v_add_f32_e32 v79, -1.0, v78
	v_sub_f32_e32 v77, v71, v77
	v_sub_f32_e32 v71, v71, v79
	v_add_f32_e32 v77, v70, v77
	v_add_f32_e32 v70, v70, v71
	v_add_f32_e32 v87, v78, v70
	v_rcp_f32_e32 v99, v87
	v_sub_f32_e32 v71, v87, v78
	v_sub_f32_e32 v98, v70, v71
	v_add_f32_e32 v71, v76, v77
	v_mul_f32_e32 v101, v71, v99
	v_sub_f32_e32 v70, v71, v76
	v_mul_f32_e32 v76, v87, v101
	v_fma_f32 v78, v101, v87, -v76
	v_fmac_f32_e32 v78, v101, v98
	v_sub_f32_e32 v100, v77, v70
	v_add_f32_e32 v70, v76, v78
	v_sub_f32_e32 v77, v71, v70
	v_pk_add_f32 v[84:85], v[70:71], v[76:77] neg_lo:[0,1] neg_hi:[0,1]
	v_mov_b32_e32 v79, v70
	v_pk_add_f32 v[70:71], v[84:85], v[78:79] neg_lo:[0,1] neg_hi:[0,1]
	s_mov_b32 s30, 0x3f317218
	v_add_f32_e32 v71, v100, v71
	v_add_f32_e32 v70, v70, v71
	v_add_f32_e32 v71, v77, v70
	v_mul_f32_e32 v100, v99, v71
	v_mul_f32_e32 v76, v87, v100
	v_fma_f32 v78, v100, v87, -v76
	v_fmac_f32_e32 v78, v100, v98
	v_sub_f32_e32 v77, v77, v71
	v_add_f32_e32 v87, v70, v77
	v_add_f32_e32 v70, v76, v78
	v_sub_f32_e32 v77, v71, v70
	v_pk_add_f32 v[84:85], v[70:71], v[76:77] neg_lo:[0,1] neg_hi:[0,1]
	v_mov_b32_e32 v79, v70
	v_pk_add_f32 v[70:71], v[84:85], v[78:79] neg_lo:[0,1] neg_hi:[0,1]
	s_nop 0
	v_add_f32_e32 v71, v87, v71
	v_add_f32_e32 v70, v70, v71
	v_add_f32_e32 v71, v101, v100
	v_add_f32_e32 v70, v77, v70
	v_sub_f32_e32 v76, v71, v101
	v_mul_f32_e32 v70, v99, v70
	v_sub_f32_e32 v76, v100, v76
	v_add_f32_e32 v76, v76, v70
	v_add_f32_e32 v78, v71, v76
	v_mul_f32_e32 v79, v78, v78
	v_fmamk_f32 v70, v79, 0x3e9b6dac, v218
	v_fmaak_f32 v171, v79, v70, 0x3f2aaada
	v_cvt_f32_i32_e32 v70, v86
	v_sub_f32_e32 v71, v78, v71
	v_sub_f32_e32 v71, v76, v71
	v_ldexp_f32 v84, v71, 1
	v_mul_f32_e32 v71, v78, v79
	v_ldexp_f32 v77, v78, 1
	v_pk_mul_f32 v[78:79], v[70:71], v[170:171]
	s_nop 0
	v_fma_f32 v76, v70, s30, -v78
	v_fmac_f32_e32 v76, 0xb102e308, v70
	v_pk_add_f32 v[70:71], v[78:79], v[76:77]
	s_mov_b32 s30, 0x7f800000
	v_sub_f32_e32 v77, v71, v77
	v_sub_f32_e32 v77, v79, v77
	v_add_f32_e32 v85, v84, v77
	v_mov_b32_e32 v84, v78
	v_pk_add_f32 v[78:79], v[70:71], v[78:79] neg_lo:[0,1] neg_hi:[0,1]
	v_pk_add_f32 v[86:87], v[70:71], v[84:85]
	v_mov_b32_e32 v77, v70
	v_mov_b32_e32 v79, v87
	v_pk_add_f32 v[98:99], v[76:77], v[78:79] neg_lo:[0,1] neg_hi:[0,1]
	v_pk_add_f32 v[76:77], v[76:77], v[78:79]
	v_mov_b32_e32 v84, v85
	v_pk_add_f32 v[78:79], v[76:77], v[70:71] op_sel:[1,0] op_sel_hi:[0,1] neg_lo:[0,1] neg_hi:[0,1]
	v_pk_add_f32 v[100:101], v[86:87], v[78:79] op_sel_hi:[1,0] neg_lo:[0,1] neg_hi:[0,1]
	v_mov_b32_e32 v86, v87
	v_mov_b32_e32 v87, v77
	v_pk_mov_b32 v[78:79], v[70:71], v[78:79] op_sel:[1,0]
	v_mov_b32_e32 v85, v70
	v_pk_add_f32 v[78:79], v[86:87], v[78:79] neg_lo:[0,1] neg_hi:[0,1]
	v_mov_b32_e32 v100, v98
	v_pk_add_f32 v[70:71], v[84:85], v[78:79] neg_lo:[0,1] neg_hi:[0,1]
	v_mov_b32_e32 v99, v77
	v_pk_add_f32 v[78:79], v[100:101], v[70:71]
	v_cmp_neq_f32_e32 vcc, s30, v69
	v_pk_add_f32 v[84:85], v[78:79], v[78:79] op_sel:[0,1] op_sel_hi:[1,0]
	s_mov_b32 s30, 0x33800000
	v_pk_add_f32 v[76:77], v[76:77], v[84:85] op_sel:[1,0] op_sel_hi:[0,1]
	v_mov_b32_e32 v79, v76
	v_pk_add_f32 v[86:87], v[78:79], v[98:99] neg_lo:[0,1] neg_hi:[0,1]
	v_mov_b32_e32 v71, v84
	v_sub_f32_e32 v77, v78, v86
	v_pk_add_f32 v[70:71], v[70:71], v[86:87] neg_lo:[0,1] neg_hi:[0,1]
	v_sub_f32_e32 v77, v98, v77
	v_add_f32_e32 v70, v70, v77
	v_add_f32_e32 v70, v70, v71
	v_add_f32_e32 v70, v76, v70
	v_cndmask_b32_e32 v70, v214, v70, vcc
	v_cmp_ngt_f32_e32 vcc, -1.0, v69
	s_nop 1
	v_cndmask_b32_e32 v70, v215, v70, vcc
	v_cmp_neq_f32_e32 vcc, -1.0, v69
	s_nop 1
	v_cndmask_b32_e32 v70, v213, v70, vcc
	v_cmp_lt_f32_e64 vcc, |v69|, s30
	s_nop 1
	v_cndmask_b32_e32 v69, v70, v69, vcc
.LBB0_341:
	s_andn2_saveexec_b64 s[0:1], s[0:1]
	s_or_b64 exec, exec, s[0:1]
	s_mov_b32 s0, 0xc1700000
	v_cmp_ngt_f32_e32 vcc, s0, v236
	v_xor_b32_e32 v70, 0x80000000, v236
	s_and_saveexec_b64 s[0:1], vcc
	s_xor_b64 s[0:1], exec, s[0:1]
	s_cbranch_execz .LBB0_343
	v_mul_f32_e32 v70, 0xbfb8aa3b, v236
	v_exp_f32_e32 v112, v70
	s_mov_b32 s30, 0x3f2aaaab
	v_add_f32_e32 v76, 1.0, v112
	v_frexp_mant_f32_e32 v78, v76
	v_cvt_f64_f32_e32 v[70:71], v76
	v_frexp_exp_i32_f64_e32 v70, v[70:71]
	v_cmp_gt_f32_e32 vcc, s30, v78
	v_add_f32_e32 v77, -1.0, v76
	v_sub_f32_e32 v79, v77, v76
	v_subbrev_co_u32_e32 v86, vcc, 0, v70, vcc
	v_sub_u32_e32 v70, 0, v86
	v_sub_f32_e32 v77, v112, v77
	v_add_f32_e32 v79, 1.0, v79
	v_ldexp_f32 v71, v76, v70
	v_add_f32_e32 v77, v77, v79
	v_add_f32_e32 v76, -1.0, v71
	v_add_f32_e32 v78, 1.0, v71
	v_ldexp_f32 v70, v77, v70
	v_add_f32_e32 v77, 1.0, v76
	v_add_f32_e32 v79, -1.0, v78
	v_sub_f32_e32 v77, v71, v77
	v_sub_f32_e32 v71, v71, v79
	v_add_f32_e32 v77, v70, v77
	v_add_f32_e32 v70, v70, v71
	v_add_f32_e32 v87, v78, v70
	v_rcp_f32_e32 v99, v87
	v_sub_f32_e32 v71, v87, v78
	v_sub_f32_e32 v98, v70, v71
	v_add_f32_e32 v71, v76, v77
	v_mul_f32_e32 v101, v71, v99
	v_sub_f32_e32 v70, v71, v76
	v_mul_f32_e32 v76, v87, v101
	v_fma_f32 v78, v101, v87, -v76
	v_fmac_f32_e32 v78, v101, v98
	v_sub_f32_e32 v100, v77, v70
	v_add_f32_e32 v70, v76, v78
	v_sub_f32_e32 v77, v71, v70
	v_pk_add_f32 v[84:85], v[70:71], v[76:77] neg_lo:[0,1] neg_hi:[0,1]
	v_mov_b32_e32 v79, v70
	v_pk_add_f32 v[70:71], v[84:85], v[78:79] neg_lo:[0,1] neg_hi:[0,1]
	s_mov_b32 s30, 0x3f317218
	v_add_f32_e32 v71, v100, v71
	v_add_f32_e32 v70, v70, v71
	v_add_f32_e32 v71, v77, v70
	v_mul_f32_e32 v100, v99, v71
	v_mul_f32_e32 v76, v87, v100
	v_fma_f32 v78, v100, v87, -v76
	v_fmac_f32_e32 v78, v100, v98
	v_sub_f32_e32 v77, v77, v71
	v_add_f32_e32 v87, v70, v77
	v_add_f32_e32 v70, v76, v78
	v_sub_f32_e32 v77, v71, v70
	v_pk_add_f32 v[84:85], v[70:71], v[76:77] neg_lo:[0,1] neg_hi:[0,1]
	v_mov_b32_e32 v79, v70
	v_pk_add_f32 v[70:71], v[84:85], v[78:79] neg_lo:[0,1] neg_hi:[0,1]
	s_nop 0
	v_add_f32_e32 v71, v87, v71
	v_add_f32_e32 v70, v70, v71
	v_add_f32_e32 v71, v101, v100
	v_add_f32_e32 v70, v77, v70
	v_sub_f32_e32 v76, v71, v101
	v_mul_f32_e32 v70, v99, v70
	v_sub_f32_e32 v76, v100, v76
	v_add_f32_e32 v76, v76, v70
	v_add_f32_e32 v78, v71, v76
	v_mul_f32_e32 v79, v78, v78
	v_fmamk_f32 v70, v79, 0x3e9b6dac, v218
	v_fmaak_f32 v171, v79, v70, 0x3f2aaada
	v_cvt_f32_i32_e32 v70, v86
	v_sub_f32_e32 v71, v78, v71
	v_sub_f32_e32 v71, v76, v71
	v_ldexp_f32 v84, v71, 1
	v_mul_f32_e32 v71, v78, v79
	v_ldexp_f32 v77, v78, 1
	v_pk_mul_f32 v[78:79], v[70:71], v[170:171]
	s_nop 0
	v_fma_f32 v76, v70, s30, -v78
	v_fmac_f32_e32 v76, 0xb102e308, v70
	v_pk_add_f32 v[70:71], v[78:79], v[76:77]
	s_mov_b32 s30, 0x7f800000
	v_sub_f32_e32 v77, v71, v77
	v_sub_f32_e32 v77, v79, v77
	v_add_f32_e32 v85, v84, v77
	v_mov_b32_e32 v84, v78
	v_pk_add_f32 v[78:79], v[70:71], v[78:79] neg_lo:[0,1] neg_hi:[0,1]
	v_pk_add_f32 v[86:87], v[70:71], v[84:85]
	v_mov_b32_e32 v77, v70
	v_mov_b32_e32 v79, v87
	v_pk_add_f32 v[98:99], v[76:77], v[78:79] neg_lo:[0,1] neg_hi:[0,1]
	v_pk_add_f32 v[76:77], v[76:77], v[78:79]
	v_mov_b32_e32 v84, v85
	v_pk_add_f32 v[78:79], v[76:77], v[70:71] op_sel:[1,0] op_sel_hi:[0,1] neg_lo:[0,1] neg_hi:[0,1]
	v_pk_add_f32 v[100:101], v[86:87], v[78:79] op_sel_hi:[1,0] neg_lo:[0,1] neg_hi:[0,1]
	v_mov_b32_e32 v86, v87
	v_mov_b32_e32 v87, v77
	v_pk_mov_b32 v[78:79], v[70:71], v[78:79] op_sel:[1,0]
	v_mov_b32_e32 v85, v70
	v_pk_add_f32 v[78:79], v[86:87], v[78:79] neg_lo:[0,1] neg_hi:[0,1]
	v_mov_b32_e32 v100, v98
	v_pk_add_f32 v[70:71], v[84:85], v[78:79] neg_lo:[0,1] neg_hi:[0,1]
	v_mov_b32_e32 v99, v77
	v_pk_add_f32 v[78:79], v[100:101], v[70:71]
	v_cmp_neq_f32_e32 vcc, s30, v112
	v_pk_add_f32 v[84:85], v[78:79], v[78:79] op_sel:[0,1] op_sel_hi:[1,0]
	s_mov_b32 s30, 0x33800000
	v_pk_add_f32 v[76:77], v[76:77], v[84:85] op_sel:[1,0] op_sel_hi:[0,1]
	v_mov_b32_e32 v79, v76
	v_pk_add_f32 v[86:87], v[78:79], v[98:99] neg_lo:[0,1] neg_hi:[0,1]
	v_mov_b32_e32 v71, v84
	v_sub_f32_e32 v77, v78, v86
	v_pk_add_f32 v[70:71], v[70:71], v[86:87] neg_lo:[0,1] neg_hi:[0,1]
	v_sub_f32_e32 v77, v98, v77
	v_add_f32_e32 v70, v70, v77
	v_add_f32_e32 v70, v70, v71
	v_add_f32_e32 v70, v76, v70
	v_cndmask_b32_e32 v70, v214, v70, vcc
	v_cmp_ngt_f32_e32 vcc, -1.0, v112
	s_nop 1
	v_cndmask_b32_e32 v70, v215, v70, vcc
	v_cmp_neq_f32_e32 vcc, -1.0, v112
	s_nop 1
	v_cndmask_b32_e32 v70, v213, v70, vcc
	v_cmp_lt_f32_e64 vcc, |v112|, s30
	s_nop 1
	v_cndmask_b32_e32 v70, v70, v112, vcc
.LBB0_343:
	s_andn2_saveexec_b64 s[0:1], s[0:1]
	s_or_b64 exec, exec, s[0:1]
	v_mov_b32_e32 v112, v238
	s_mov_b32 s0, 0xc1700000
	v_cmp_ngt_f32_e32 vcc, s0, v237
	v_xor_b32_e32 v71, 0x80000000, v237
	s_and_saveexec_b64 s[0:1], vcc
	s_xor_b64 s[0:1], exec, s[0:1]
	s_cbranch_execz .LBB0_326
	v_mul_f32_e32 v71, 0xbfb8aa3b, v237
	v_exp_f32_e32 v71, v71
	s_mov_b32 s30, 0x3f2aaaab
	v_add_f32_e32 v78, 1.0, v71
	v_frexp_mant_f32_e32 v84, v78
	v_cvt_f64_f32_e32 v[76:77], v78
	v_frexp_exp_i32_f64_e32 v76, v[76:77]
	v_cmp_gt_f32_e32 vcc, s30, v84
	v_add_f32_e32 v79, -1.0, v78
	v_sub_f32_e32 v85, v79, v78
	v_subbrev_co_u32_e32 v98, vcc, 0, v76, vcc
	v_sub_u32_e32 v76, 0, v98
	v_sub_f32_e32 v79, v71, v79
	v_add_f32_e32 v85, 1.0, v85
	v_ldexp_f32 v77, v78, v76
	v_add_f32_e32 v79, v79, v85
	v_add_f32_e32 v78, -1.0, v77
	v_add_f32_e32 v84, 1.0, v77
	v_ldexp_f32 v76, v79, v76
	v_add_f32_e32 v79, 1.0, v78
	v_add_f32_e32 v85, -1.0, v84
	v_sub_f32_e32 v79, v77, v79
	v_sub_f32_e32 v77, v77, v85
	v_add_f32_e32 v79, v76, v79
	v_add_f32_e32 v76, v76, v77
	v_add_f32_e32 v99, v84, v76
	v_rcp_f32_e32 v101, v99
	v_sub_f32_e32 v77, v99, v84
	v_sub_f32_e32 v100, v76, v77
	v_add_f32_e32 v77, v78, v79
	v_mul_f32_e32 v119, v77, v101
	v_sub_f32_e32 v76, v77, v78
	v_mul_f32_e32 v78, v99, v119
	v_fma_f32 v84, v119, v99, -v78
	v_fmac_f32_e32 v84, v119, v100
	v_sub_f32_e32 v118, v79, v76
	v_add_f32_e32 v76, v78, v84
	v_sub_f32_e32 v79, v77, v76
	v_pk_add_f32 v[86:87], v[76:77], v[78:79] neg_lo:[0,1] neg_hi:[0,1]
	v_mov_b32_e32 v85, v76
	v_pk_add_f32 v[76:77], v[86:87], v[84:85] neg_lo:[0,1] neg_hi:[0,1]
	s_mov_b32 s30, 0x3f317218
	v_add_f32_e32 v77, v118, v77
	v_add_f32_e32 v76, v76, v77
	v_add_f32_e32 v77, v79, v76
	v_mul_f32_e32 v118, v101, v77
	v_mul_f32_e32 v78, v99, v118
	v_fma_f32 v84, v118, v99, -v78
	v_fmac_f32_e32 v84, v118, v100
	v_sub_f32_e32 v79, v79, v77
	v_add_f32_e32 v99, v76, v79
	v_add_f32_e32 v76, v78, v84
	v_sub_f32_e32 v79, v77, v76
	v_pk_add_f32 v[86:87], v[76:77], v[78:79] neg_lo:[0,1] neg_hi:[0,1]
	v_mov_b32_e32 v85, v76
	v_pk_add_f32 v[76:77], v[86:87], v[84:85] neg_lo:[0,1] neg_hi:[0,1]
	s_nop 0
	v_add_f32_e32 v77, v99, v77
	v_add_f32_e32 v76, v76, v77
	v_add_f32_e32 v77, v119, v118
	v_add_f32_e32 v76, v79, v76
	v_sub_f32_e32 v78, v77, v119
	v_mul_f32_e32 v76, v101, v76
	v_sub_f32_e32 v78, v118, v78
	v_add_f32_e32 v78, v78, v76
	v_add_f32_e32 v84, v77, v78
	v_mul_f32_e32 v85, v84, v84
	v_fmamk_f32 v76, v85, 0x3e9b6dac, v218
	v_fmaak_f32 v171, v85, v76, 0x3f2aaada
	v_cvt_f32_i32_e32 v76, v98
	v_sub_f32_e32 v77, v84, v77
	v_sub_f32_e32 v77, v78, v77
	v_ldexp_f32 v86, v77, 1
	v_mul_f32_e32 v77, v84, v85
	v_ldexp_f32 v79, v84, 1
	v_pk_mul_f32 v[84:85], v[76:77], v[170:171]
	s_nop 0
	v_fma_f32 v78, v76, s30, -v84
	v_fmac_f32_e32 v78, 0xb102e308, v76
	v_pk_add_f32 v[76:77], v[84:85], v[78:79]
	s_mov_b32 s30, 0x7f800000
	v_sub_f32_e32 v79, v77, v79
	v_sub_f32_e32 v79, v85, v79
	v_add_f32_e32 v87, v86, v79
	v_mov_b32_e32 v86, v84
	v_pk_add_f32 v[84:85], v[76:77], v[84:85] neg_lo:[0,1] neg_hi:[0,1]
	v_pk_add_f32 v[98:99], v[76:77], v[86:87]
	v_mov_b32_e32 v79, v76
	v_mov_b32_e32 v85, v99
	v_pk_add_f32 v[100:101], v[78:79], v[84:85] neg_lo:[0,1] neg_hi:[0,1]
	v_pk_add_f32 v[78:79], v[78:79], v[84:85]
	v_mov_b32_e32 v86, v87
	v_pk_add_f32 v[84:85], v[78:79], v[76:77] op_sel:[1,0] op_sel_hi:[0,1] neg_lo:[0,1] neg_hi:[0,1]
	v_pk_add_f32 v[118:119], v[98:99], v[84:85] op_sel_hi:[1,0] neg_lo:[0,1] neg_hi:[0,1]
	v_mov_b32_e32 v98, v99
	v_mov_b32_e32 v99, v79
	v_pk_mov_b32 v[84:85], v[76:77], v[84:85] op_sel:[1,0]
	v_mov_b32_e32 v87, v76
	v_pk_add_f32 v[84:85], v[98:99], v[84:85] neg_lo:[0,1] neg_hi:[0,1]
	v_mov_b32_e32 v118, v100
	v_pk_add_f32 v[76:77], v[86:87], v[84:85] neg_lo:[0,1] neg_hi:[0,1]
	v_mov_b32_e32 v101, v79
	v_pk_add_f32 v[84:85], v[118:119], v[76:77]
	v_cmp_neq_f32_e32 vcc, s30, v71
	v_pk_add_f32 v[86:87], v[84:85], v[84:85] op_sel:[0,1] op_sel_hi:[1,0]
	s_mov_b32 s30, 0x33800000
	v_pk_add_f32 v[78:79], v[78:79], v[86:87] op_sel:[1,0] op_sel_hi:[0,1]
	v_mov_b32_e32 v85, v78
	v_pk_add_f32 v[98:99], v[84:85], v[100:101] neg_lo:[0,1] neg_hi:[0,1]
	v_mov_b32_e32 v77, v86
	v_sub_f32_e32 v79, v84, v98
	v_pk_add_f32 v[76:77], v[76:77], v[98:99] neg_lo:[0,1] neg_hi:[0,1]
	v_sub_f32_e32 v79, v100, v79
	v_add_f32_e32 v76, v76, v79
	v_add_f32_e32 v76, v76, v77
	v_add_f32_e32 v76, v78, v76
	v_cndmask_b32_e32 v76, v214, v76, vcc
	v_cmp_ngt_f32_e32 vcc, -1.0, v71
	s_nop 1
	v_cndmask_b32_e32 v76, v215, v76, vcc
	v_cmp_neq_f32_e32 vcc, -1.0, v71
	s_nop 1
	v_cndmask_b32_e32 v76, v213, v76, vcc
	v_cmp_lt_f32_e64 vcc, |v71|, s30
	s_nop 1
	v_cndmask_b32_e32 v71, v76, v71, vcc
	s_branch .LBB0_326
